# v080: v078 + each k_inv epilogue touches the next unit's row-statistics lines (KRSQ) so that the next epilogue's loads hit L2
# speedup vs baseline: 1.0004x; 1.0004x over previous
.LBB0_394:
	s_add_u32 s34, s20, s24
	s_addc_u32 s35, s21, s25
	s_add_u32 s36, s34, 0x100
	s_addc_u32 s37, s35, 0
	s_and_b64 s[30:31], s[28:29], exec
	s_cselect_b32 s39, s15, s37
	s_cselect_b32 s38, s14, s36
	s_add_u32 s24, s6, s24
	s_addc_u32 s25, s7, s25
	s_add_u32 s30, s24, 0x100
	s_addc_u32 s31, s25, 0
	s_add_u32 s24, s38, 0x80
	s_addc_u32 s25, s39, 0
	s_and_b64 s[28:29], s[28:29], exec
	s_cselect_b32 s41, s1, s31
	s_cselect_b32 s40, s13, s30
	s_add_u32 s42, s34, 0x12080
	s_addc_u32 s43, s35, 0
	s_add_i32 s78, s63, s49
	s_add_i32 m0, s50, 0xc000
	s_add_i32 s79, s50, 0xe000
	s_add_i32 s77, s78, 0x2000
	s_add_u32 s36, s40, 0x10000
	s_addc_u32 s37, s41, 0
	s_add_i32 s75, s64, s49
	s_add_i32 s73, s75, 0x2000
	s_add_i32 s72, 0, 0x18000
	s_add_u32 s34, s38, 0x12000
	ds_read_b128 v[146:149], v140
	ds_read_b128 v[150:153], v140 offset:1024
	ds_read_b128 v[154:157], v140 offset:2048
	ds_read_b128 v[158:161], v140 offset:3072
	s_addc_u32 s35, s39, 0
	s_add_i32 s70, 0, 0x1c000
	s_add_u32 s30, s40, 0x80
	s_addc_u32 s31, s41, 0
	s_add_i32 s71, s72, s49
	s_add_i32 s69, s71, 0x2000
	s_add_u32 s28, s40, 0x10080
	s_addc_u32 s29, s41, 0
	s_add_i32 s76, s70, s49
	s_add_i32 s74, s76, 0x2000
	ds_read_b128 v[162:165], v141
	ds_read_b128 v[166:169], v141 offset:1024
	ds_read_b128 v[170:173], v141 offset:2048
	ds_read_b128 v[174:177], v141 offset:3072
	ds_read_b128 v[178:181], v141 offset:4096
	ds_read_b128 v[182:185], v141 offset:5120
	ds_read_b128 v[186:189], v141 offset:6144
	ds_read_b128 v[190:193], v141 offset:7168
	s_nop 0
	global_load_lds_dwordx4 v130, s[42:43]
	s_mov_b32 m0, s79
	s_nop 0
	global_load_lds_dwordx4 v134, s[42:43]
	s_waitcnt lgkmcnt(8)
	s_barrier
	s_waitcnt lgkmcnt(0)
	s_setprio 1
	s_waitcnt lgkmcnt(0)
	v_mfma_f32_16x16x32_bf16 v[126:129], v[146:149], v[162:165], v[126:129]
	v_mfma_f32_16x16x32_bf16 v[122:125], v[154:157], v[162:165], v[122:125]
	v_mfma_f32_16x16x32_bf16 v[110:113], v[146:149], v[170:173], v[110:113]
	v_mfma_f32_16x16x32_bf16 v[106:109], v[154:157], v[170:173], v[106:109]
	v_mfma_f32_16x16x32_bf16 v[94:97], v[146:149], v[178:181], v[94:97]
	v_mfma_f32_16x16x32_bf16 v[90:93], v[154:157], v[178:181], v[90:93]
	v_mfma_f32_16x16x32_bf16 v[78:81], v[146:149], v[186:189], v[78:81]
	v_mfma_f32_16x16x32_bf16 v[74:77], v[154:157], v[186:189], v[74:77]
	v_mfma_f32_16x16x32_bf16 v[126:129], v[150:153], v[166:169], v[126:129]
	v_mfma_f32_16x16x32_bf16 v[122:125], v[158:161], v[166:169], v[122:125]
	v_mfma_f32_16x16x32_bf16 v[110:113], v[150:153], v[174:177], v[110:113]
	v_mfma_f32_16x16x32_bf16 v[106:109], v[158:161], v[174:177], v[106:109]
	v_mfma_f32_16x16x32_bf16 v[94:97], v[150:153], v[182:185], v[94:97]
	v_mfma_f32_16x16x32_bf16 v[90:93], v[158:161], v[182:185], v[90:93]
	v_mfma_f32_16x16x32_bf16 v[78:81], v[150:153], v[190:193], v[78:81]
	v_mfma_f32_16x16x32_bf16 v[74:77], v[158:161], v[190:193], v[74:77]
	s_setprio 0
	s_barrier
	s_mov_b32 m0, s78
	ds_read_b128 v[194:197], v142
	ds_read_b128 v[198:201], v142 offset:1024
	ds_read_b128 v[202:205], v142 offset:2048
	ds_read_b128 v[206:209], v142 offset:3072
	s_nop 0
	global_load_lds_dwordx4 v132, s[40:41]
	s_mov_b32 m0, s77
	s_nop 0
	global_load_lds_dwordx4 v136, s[40:41]
	s_barrier
	s_waitcnt lgkmcnt(0)
	s_setprio 1
	s_waitcnt lgkmcnt(0)
	v_mfma_f32_16x16x32_bf16 v[118:121], v[194:197], v[162:165], v[118:121]
	v_mfma_f32_16x16x32_bf16 v[114:117], v[202:205], v[162:165], v[114:117]
	v_mfma_f32_16x16x32_bf16 v[102:105], v[194:197], v[170:173], v[102:105]
	v_mfma_f32_16x16x32_bf16 v[98:101], v[202:205], v[170:173], v[98:101]
	v_mfma_f32_16x16x32_bf16 v[86:89], v[194:197], v[178:181], v[86:89]
	v_mfma_f32_16x16x32_bf16 v[82:85], v[202:205], v[178:181], v[82:85]
	v_mfma_f32_16x16x32_bf16 v[70:73], v[194:197], v[186:189], v[70:73]
	v_mfma_f32_16x16x32_bf16 v[66:69], v[202:205], v[186:189], v[66:69]
	v_mfma_f32_16x16x32_bf16 v[118:121], v[198:201], v[166:169], v[118:121]
	v_mfma_f32_16x16x32_bf16 v[114:117], v[206:209], v[166:169], v[114:117]
	v_mfma_f32_16x16x32_bf16 v[102:105], v[198:201], v[174:177], v[102:105]
	v_mfma_f32_16x16x32_bf16 v[98:101], v[206:209], v[174:177], v[98:101]
	v_mfma_f32_16x16x32_bf16 v[86:89], v[198:201], v[182:185], v[86:89]
	v_mfma_f32_16x16x32_bf16 v[82:85], v[206:209], v[182:185], v[82:85]
	v_mfma_f32_16x16x32_bf16 v[70:73], v[198:201], v[190:193], v[70:73]
	v_mfma_f32_16x16x32_bf16 v[66:69], v[206:209], v[190:193], v[66:69]
	s_setprio 0
	s_mov_b32 m0, s50
	s_barrier
	ds_read_b128 v[162:165], v141 offset:16384
	ds_read_b128 v[166:169], v141 offset:17408
	ds_read_b128 v[170:173], v141 offset:18432
	ds_read_b128 v[174:177], v141 offset:19456
	ds_read_b128 v[178:181], v141 offset:20480
	ds_read_b128 v[182:185], v141 offset:21504
	ds_read_b128 v[186:189], v141 offset:22528
	ds_read_b128 v[190:193], v141 offset:23552
	s_nop 0
	global_load_lds_dwordx4 v130, s[38:39]
	s_mov_b32 m0, s51
	s_nop 0
	global_load_lds_dwordx4 v134, s[38:39]
	s_barrier
	s_waitcnt lgkmcnt(0)
	s_setprio 1
	s_waitcnt lgkmcnt(0)
	v_mfma_f32_16x16x32_bf16 v[62:65], v[146:149], v[162:165], v[62:65]
	v_mfma_f32_16x16x32_bf16 v[58:61], v[154:157], v[162:165], v[58:61]
	v_mfma_f32_16x16x32_bf16 v[46:49], v[146:149], v[170:173], v[46:49]
	v_mfma_f32_16x16x32_bf16 v[42:45], v[154:157], v[170:173], v[42:45]
	v_mfma_f32_16x16x32_bf16 v[30:33], v[146:149], v[178:181], v[30:33]
	v_mfma_f32_16x16x32_bf16 v[26:29], v[154:157], v[178:181], v[26:29]
	v_mfma_f32_16x16x32_bf16 v[14:17], v[146:149], v[186:189], v[14:17]
	v_mfma_f32_16x16x32_bf16 v[10:13], v[154:157], v[186:189], v[10:13]
	v_mfma_f32_16x16x32_bf16 v[62:65], v[150:153], v[166:169], v[62:65]
	v_mfma_f32_16x16x32_bf16 v[58:61], v[158:161], v[166:169], v[58:61]
	v_mfma_f32_16x16x32_bf16 v[46:49], v[150:153], v[174:177], v[46:49]
	v_mfma_f32_16x16x32_bf16 v[42:45], v[158:161], v[174:177], v[42:45]
	v_mfma_f32_16x16x32_bf16 v[30:33], v[150:153], v[182:185], v[30:33]
	v_mfma_f32_16x16x32_bf16 v[26:29], v[158:161], v[182:185], v[26:29]
	v_mfma_f32_16x16x32_bf16 v[14:17], v[150:153], v[190:193], v[14:17]
	v_mfma_f32_16x16x32_bf16 v[10:13], v[158:161], v[190:193], v[10:13]
	s_setprio 0
	s_barrier
	s_mov_b32 m0, s75
	s_nop 0
	global_load_lds_dwordx4 v132, s[36:37]
	s_mov_b32 m0, s73
	s_nop 0
	global_load_lds_dwordx4 v136, s[36:37]
	s_waitcnt vmcnt(6)
	s_barrier
	s_setprio 1
	v_mfma_f32_16x16x32_bf16 v[54:57], v[194:197], v[162:165], v[54:57]
	v_mfma_f32_16x16x32_bf16 v[50:53], v[202:205], v[162:165], v[50:53]
	v_mfma_f32_16x16x32_bf16 v[38:41], v[194:197], v[170:173], v[38:41]
	v_mfma_f32_16x16x32_bf16 v[34:37], v[202:205], v[170:173], v[34:37]
	v_mfma_f32_16x16x32_bf16 v[22:25], v[194:197], v[178:181], v[22:25]
	v_mfma_f32_16x16x32_bf16 v[18:21], v[202:205], v[178:181], v[18:21]
	v_mfma_f32_16x16x32_bf16 v[6:9], v[194:197], v[186:189], v[6:9]
	v_mfma_f32_16x16x32_bf16 v[2:5], v[202:205], v[186:189], v[2:5]
	v_mfma_f32_16x16x32_bf16 v[54:57], v[198:201], v[166:169], v[54:57]
	v_mfma_f32_16x16x32_bf16 v[50:53], v[206:209], v[166:169], v[50:53]
	v_mfma_f32_16x16x32_bf16 v[38:41], v[198:201], v[174:177], v[38:41]
	v_mfma_f32_16x16x32_bf16 v[34:37], v[206:209], v[174:177], v[34:37]
	v_mfma_f32_16x16x32_bf16 v[22:25], v[198:201], v[182:185], v[22:25]
	v_mfma_f32_16x16x32_bf16 v[18:21], v[206:209], v[182:185], v[18:21]
	v_mfma_f32_16x16x32_bf16 v[6:9], v[198:201], v[190:193], v[6:9]
	v_mfma_f32_16x16x32_bf16 v[2:5], v[206:209], v[190:193], v[2:5]
	s_setprio 0
	v_add_u32_e32 v138, s72, v1
	s_barrier
	ds_read_b128 v[146:149], v138
	ds_read_b128 v[150:153], v138 offset:1024
	ds_read_b128 v[154:157], v138 offset:2048
	ds_read_b128 v[158:161], v138 offset:3072
	s_mov_b32 m0, s52
	ds_read_b128 v[162:165], v141 offset:32768
	ds_read_b128 v[166:169], v141 offset:33792
	ds_read_b128 v[170:173], v141 offset:34816
	ds_read_b128 v[174:177], v141 offset:35840
	ds_read_b128 v[178:181], v141 offset:36864
	ds_read_b128 v[182:185], v141 offset:37888
	ds_read_b128 v[186:189], v141 offset:38912
	ds_read_b128 v[190:193], v141 offset:39936
	s_nop 0
	global_load_lds_dwordx4 v130, s[34:35]
	s_mov_b32 m0, s53
	s_nop 0
	global_load_lds_dwordx4 v134, s[34:35]
	s_waitcnt lgkmcnt(8)
	s_barrier
	s_waitcnt lgkmcnt(0)
	s_setprio 1
	s_waitcnt lgkmcnt(0)
	v_mfma_f32_16x16x32_bf16 v[126:129], v[146:149], v[162:165], v[126:129]
	v_mfma_f32_16x16x32_bf16 v[122:125], v[154:157], v[162:165], v[122:125]
	v_mfma_f32_16x16x32_bf16 v[110:113], v[146:149], v[170:173], v[110:113]
	v_mfma_f32_16x16x32_bf16 v[106:109], v[154:157], v[170:173], v[106:109]
	v_mfma_f32_16x16x32_bf16 v[94:97], v[146:149], v[178:181], v[94:97]
	v_mfma_f32_16x16x32_bf16 v[90:93], v[154:157], v[178:181], v[90:93]
	v_mfma_f32_16x16x32_bf16 v[78:81], v[146:149], v[186:189], v[78:81]
	v_mfma_f32_16x16x32_bf16 v[74:77], v[154:157], v[186:189], v[74:77]
	v_mfma_f32_16x16x32_bf16 v[126:129], v[150:153], v[166:169], v[126:129]
	v_mfma_f32_16x16x32_bf16 v[122:125], v[158:161], v[166:169], v[122:125]
	v_mfma_f32_16x16x32_bf16 v[110:113], v[150:153], v[174:177], v[110:113]
	v_mfma_f32_16x16x32_bf16 v[106:109], v[158:161], v[174:177], v[106:109]
	v_mfma_f32_16x16x32_bf16 v[94:97], v[150:153], v[182:185], v[94:97]
	v_mfma_f32_16x16x32_bf16 v[90:93], v[158:161], v[182:185], v[90:93]
	v_mfma_f32_16x16x32_bf16 v[78:81], v[150:153], v[190:193], v[78:81]
	v_mfma_f32_16x16x32_bf16 v[74:77], v[158:161], v[190:193], v[74:77]
	s_setprio 0
	s_barrier
	v_add_u32_e32 v138, s70, v1
	s_mov_b32 m0, s71
	ds_read_b128 v[194:197], v138
	ds_read_b128 v[198:201], v138 offset:1024
	ds_read_b128 v[202:205], v138 offset:2048
	ds_read_b128 v[206:209], v138 offset:3072
	s_nop 0
	global_load_lds_dwordx4 v132, s[30:31]
	s_mov_b32 m0, s69
	s_nop 0
	global_load_lds_dwordx4 v136, s[30:31]
	s_barrier
	s_waitcnt lgkmcnt(0)
	s_setprio 1
	s_waitcnt lgkmcnt(0)
	v_mfma_f32_16x16x32_bf16 v[118:121], v[194:197], v[162:165], v[118:121]
	v_mfma_f32_16x16x32_bf16 v[114:117], v[202:205], v[162:165], v[114:117]
	v_mfma_f32_16x16x32_bf16 v[102:105], v[194:197], v[170:173], v[102:105]
	v_mfma_f32_16x16x32_bf16 v[98:101], v[202:205], v[170:173], v[98:101]
	v_mfma_f32_16x16x32_bf16 v[86:89], v[194:197], v[178:181], v[86:89]
	v_mfma_f32_16x16x32_bf16 v[82:85], v[202:205], v[178:181], v[82:85]
	v_mfma_f32_16x16x32_bf16 v[70:73], v[194:197], v[186:189], v[70:73]
	v_mfma_f32_16x16x32_bf16 v[66:69], v[202:205], v[186:189], v[66:69]
	v_mfma_f32_16x16x32_bf16 v[118:121], v[198:201], v[166:169], v[118:121]
	v_mfma_f32_16x16x32_bf16 v[114:117], v[206:209], v[166:169], v[114:117]
	v_mfma_f32_16x16x32_bf16 v[102:105], v[198:201], v[174:177], v[102:105]
	v_mfma_f32_16x16x32_bf16 v[98:101], v[206:209], v[174:177], v[98:101]
	v_mfma_f32_16x16x32_bf16 v[86:89], v[198:201], v[182:185], v[86:89]
	v_mfma_f32_16x16x32_bf16 v[82:85], v[206:209], v[182:185], v[82:85]
	v_mfma_f32_16x16x32_bf16 v[70:73], v[198:201], v[190:193], v[70:73]
	v_mfma_f32_16x16x32_bf16 v[66:69], v[206:209], v[190:193], v[66:69]
	s_setprio 0
	s_mov_b32 m0, s58
	s_barrier
	ds_read_b128 v[162:165], v141 offset:49152
	ds_read_b128 v[166:169], v141 offset:50176
	ds_read_b128 v[170:173], v141 offset:51200
	ds_read_b128 v[174:177], v141 offset:52224
	ds_read_b128 v[178:181], v141 offset:53248
	ds_read_b128 v[182:185], v141 offset:54272
	ds_read_b128 v[186:189], v141 offset:55296
	ds_read_b128 v[190:193], v141 offset:56320
	s_nop 0
	global_load_lds_dwordx4 v130, s[24:25]
	s_mov_b32 m0, s59
	s_nop 0
	global_load_lds_dwordx4 v134, s[24:25]
	s_barrier
	s_waitcnt lgkmcnt(0)
	s_setprio 1
	s_waitcnt lgkmcnt(0)
	v_mfma_f32_16x16x32_bf16 v[62:65], v[146:149], v[162:165], v[62:65]
	v_mfma_f32_16x16x32_bf16 v[58:61], v[154:157], v[162:165], v[58:61]
	v_mfma_f32_16x16x32_bf16 v[46:49], v[146:149], v[170:173], v[46:49]
	v_mfma_f32_16x16x32_bf16 v[42:45], v[154:157], v[170:173], v[42:45]
	v_mfma_f32_16x16x32_bf16 v[30:33], v[146:149], v[178:181], v[30:33]
	v_mfma_f32_16x16x32_bf16 v[26:29], v[154:157], v[178:181], v[26:29]
	v_mfma_f32_16x16x32_bf16 v[14:17], v[146:149], v[186:189], v[14:17]
	v_mfma_f32_16x16x32_bf16 v[10:13], v[154:157], v[186:189], v[10:13]
	v_mfma_f32_16x16x32_bf16 v[62:65], v[150:153], v[166:169], v[62:65]
	v_mfma_f32_16x16x32_bf16 v[58:61], v[158:161], v[166:169], v[58:61]
	v_mfma_f32_16x16x32_bf16 v[46:49], v[150:153], v[174:177], v[46:49]
	v_mfma_f32_16x16x32_bf16 v[42:45], v[158:161], v[174:177], v[42:45]
	v_mfma_f32_16x16x32_bf16 v[30:33], v[150:153], v[182:185], v[30:33]
	v_mfma_f32_16x16x32_bf16 v[26:29], v[158:161], v[182:185], v[26:29]
	v_mfma_f32_16x16x32_bf16 v[14:17], v[150:153], v[190:193], v[14:17]
	v_mfma_f32_16x16x32_bf16 v[10:13], v[158:161], v[190:193], v[10:13]
	s_setprio 0
	s_barrier
	s_mov_b32 m0, s76
	s_nop 0
	global_load_lds_dwordx4 v132, s[28:29]
	s_mov_b32 m0, s74
	s_nop 0
	global_load_lds_dwordx4 v136, s[28:29]
	s_waitcnt vmcnt(6)
	s_barrier
	s_setprio 1
	v_mfma_f32_16x16x32_bf16 v[54:57], v[194:197], v[162:165], v[54:57]
	v_mfma_f32_16x16x32_bf16 v[50:53], v[202:205], v[162:165], v[50:53]
	v_mfma_f32_16x16x32_bf16 v[38:41], v[194:197], v[170:173], v[38:41]
	v_mfma_f32_16x16x32_bf16 v[34:37], v[202:205], v[170:173], v[34:37]
	v_mfma_f32_16x16x32_bf16 v[22:25], v[194:197], v[178:181], v[22:25]
	v_mfma_f32_16x16x32_bf16 v[18:21], v[202:205], v[178:181], v[18:21]
	v_mfma_f32_16x16x32_bf16 v[6:9], v[194:197], v[186:189], v[6:9]
	v_mfma_f32_16x16x32_bf16 v[2:5], v[202:205], v[186:189], v[2:5]
	v_mfma_f32_16x16x32_bf16 v[54:57], v[198:201], v[166:169], v[54:57]
	v_mfma_f32_16x16x32_bf16 v[50:53], v[206:209], v[166:169], v[50:53]
	v_mfma_f32_16x16x32_bf16 v[38:41], v[198:201], v[174:177], v[38:41]
	v_mfma_f32_16x16x32_bf16 v[34:37], v[206:209], v[174:177], v[34:37]
	v_mfma_f32_16x16x32_bf16 v[22:25], v[198:201], v[182:185], v[22:25]
	v_mfma_f32_16x16x32_bf16 v[18:21], v[206:209], v[182:185], v[18:21]
	v_mfma_f32_16x16x32_bf16 v[6:9], v[198:201], v[190:193], v[6:9]
	v_mfma_f32_16x16x32_bf16 v[2:5], v[206:209], v[190:193], v[2:5]
	s_setprio 0
	s_andn2_b64 vcc, exec, s[22:23]
	s_mov_b64 s[28:29], -1
	s_mov_b64 s[22:23], 0
	s_mov_b64 s[24:25], 0x100
	s_barrier
	s_cbranch_vccz .LBB0_394
	v_mov_b32_e32 v154, v0
	s_ashr_i32 s1, s0, 31
	v_readfirstlane_b32 s6, v154
	s_bfe_u32 s13, s6, 0x20006
	s_ashr_i32 s6, s6, 2
	s_andn2_b32 s6, s6, 63
	s_ashr_i32 s7, s6, 31
	s_lshl_b64 s[20:21], s[0:1], 10
	s_add_u32 s22, s54, s20
	s_addc_u32 s23, s55, s21
	s_lshl_b64 s[20:21], s[6:7], 2
	v_and_b32_e32 v145, 15, v154
	s_add_u32 s20, s22, s20
	s_addc_u32 s21, s23, s21
	v_lshlrev_b32_e32 v138, 2, v145
	s_min_u32 s100, s67, 0x7ff
	s_lshl_b32 s100, s100, 10
	v_and_b32_e32 v210, 7, v0
	v_lshlrev_b32_e32 v210, 7, v210
	v_add_u32_e32 v210, s100, v210
	global_load_dword v211, v210, s[54:55]
	global_load_dword v153, v138, s[20:21] offset:64
	global_load_dword v152, v138, s[20:21] offset:128
	global_load_dword v151, v138, s[20:21] offset:192
	global_load_dword v150, v138, s[20:21] offset:512
	global_load_dword v149, v138, s[20:21] offset:576
	global_load_dword v148, v138, s[20:21] offset:640
	global_load_dword v147, v138, s[20:21] offset:704
	v_mul_f32_e32 v127, v127, v127
	v_mul_f32_e32 v123, v123, v123
	v_mul_f32_e32 v119, v119, v119
	v_mul_f32_e32 v115, v115, v115
	v_fmac_f32_e32 v127, v126, v126
	v_mul_f32_e32 v126, v129, v129
	v_fmac_f32_e32 v123, v122, v122
	v_mul_f32_e32 v122, v125, v125
	v_fmac_f32_e32 v119, v118, v118
	v_mul_f32_e32 v118, v121, v121
	v_fmac_f32_e32 v115, v114, v114
	v_mul_f32_e32 v114, v117, v117
	v_fmac_f32_e32 v126, v128, v128
	v_fmac_f32_e32 v122, v124, v124
	v_fmac_f32_e32 v118, v120, v120
	v_fmac_f32_e32 v114, v116, v116
	v_add_f32_e32 v126, v127, v126
	v_add_f32_e32 v122, v123, v122
	v_add_f32_e32 v118, v119, v118
	v_add_f32_e32 v114, v115, v114
	v_add_f32_e32 v122, v126, v122
	v_add_f32_e32 v114, v118, v114
	v_add_f32_e32 v115, v122, v114
	v_mov_b32_e32 v116, v115
	s_nop 1
	v_permlane16_swap_b32 v116, v115
	v_and_b32_e32 v156, 64, v143
	v_xor_b32_e32 v155, 32, v143
	v_add_u32_e32 v156, 64, v156
	v_cmp_lt_i32_e32 vcc, v155, v156
	s_lshl_b32 s22, s68, 2
	s_or_b32 s22, s13, s22
	v_cndmask_b32_e32 v114, v143, v155, vcc
	s_lshl_b64 s[0:1], s[0:1], 8
	v_lshlrev_b32_e32 v114, 2, v114
	s_waitcnt lgkmcnt(0)
	v_add_f32_e32 v115, v115, v116
	s_add_u32 s0, s0, s6
	v_mov_b32_e32 v116, v115
	s_nop 1
	v_permlane32_swap_b32 v116, v115
	s_addc_u32 s1, s1, s7
	s_ashr_i32 s23, s22, 31
	v_or_b32_e32 v146, s0, v145
	v_mov_b32_e32 v145, s1
	s_lshl_b64 s[0:1], s[22:23], 2
	v_and_b32_e32 v117, 48, v154
	s_add_u32 s0, s56, s0
	v_cmp_eq_u32_e64 s[6:7], 0, v117
	s_addc_u32 s1, s57, s1
	s_and_saveexec_b64 s[22:23], s[6:7]
	s_cbranch_execz .LBB0_397
	v_lshl_add_u64 v[118:119], s[20:21], 0, v[138:139]
	global_load_dword v118, v[118:119], off
	s_waitcnt lgkmcnt(0)
	v_add_f32_e32 v115, v115, v116
	v_mad_u64_u32 v[116:117], s[20:21], v146, 48, s[0:1]
	s_waitcnt vmcnt(0)
	v_add_f32_e32 v115, v115, v118
	v_fmamk_f32 v115, v115, 0x3c2aaaab, v144
	v_mul_f32_e32 v118, 0x4b800000, v115
	v_cmp_gt_f32_e32 vcc, s65, v115
	s_nop 1
	v_cndmask_b32_e32 v115, v115, v118, vcc
	v_rsq_f32_e32 v115, v115
	v_mov_b32_e32 v118, v117
	v_mad_u64_u32 v[118:119], s[20:21], v145, 48, v[118:119]
	v_mul_f32_e32 v117, 0x45800000, v115
	v_cndmask_b32_e32 v115, v115, v117, vcc
	v_mov_b32_e32 v117, v118
	global_store_dword v[116:117], v115, off

.LBB0_654:
	s_add_u32 s36, s14, s26
	s_addc_u32 s37, s15, s27
	s_add_u32 s38, s36, 0x100
	s_addc_u32 s39, s37, 0
	s_and_b64 s[30:31], s[28:29], exec
	s_cselect_b32 s41, s19, s39
	s_cselect_b32 s40, s18, s38
	s_add_u32 s26, s0, s26
	s_addc_u32 s27, s1, s27
	s_add_u32 s30, s26, 0x100
	s_addc_u32 s31, s27, 0
	s_add_u32 s26, s40, 0x80
	s_addc_u32 s27, s41, 0
	s_add_i32 s81, 0, 0x10000
	s_and_b64 s[28:29], s[28:29], exec
	s_cselect_b32 s43, s17, s31
	s_cselect_b32 s42, s23, s30
	s_add_u32 s44, s36, 0x12080
	s_addc_u32 s45, s37, 0
	s_add_i32 s86, s81, s51
	s_add_i32 m0, s52, 0xc000
	s_add_i32 s87, s52, 0xe000
	s_add_i32 s85, 0, 0x14000
	s_add_i32 s84, s86, 0x2000
	s_add_u32 s38, s42, 0x10000
	s_addc_u32 s39, s43, 0
	s_add_i32 s82, s85, s51
	s_add_i32 s80, s82, 0x2000
	s_add_i32 s79, 0, 0x18000
	v_add_u32_e32 v152, s81, v1
	s_add_u32 s36, s40, 0x12000
	ds_read_b128 v[140:143], v152
	ds_read_b128 v[144:147], v152 offset:1024
	ds_read_b128 v[148:151], v152 offset:2048
	ds_read_b128 v[152:155], v152 offset:3072
	s_addc_u32 s37, s41, 0
	s_add_i32 s75, 0, 0x1c000
	s_add_u32 s30, s42, 0x80
	s_addc_u32 s31, s43, 0
	s_add_i32 s78, s79, s51
	s_add_i32 s74, s78, 0x2000
	s_add_u32 s28, s42, 0x10080
	s_addc_u32 s29, s43, 0
	s_add_i32 s83, s75, s51
	s_add_i32 s81, s83, 0x2000
	ds_read_b128 v[156:159], v3
	ds_read_b128 v[160:163], v3 offset:1024
	ds_read_b128 v[164:167], v3 offset:2048
	ds_read_b128 v[168:171], v3 offset:3072
	ds_read_b128 v[172:175], v3 offset:4096
	ds_read_b128 v[176:179], v3 offset:5120
	ds_read_b128 v[180:183], v3 offset:6144
	ds_read_b128 v[184:187], v3 offset:7168
	s_nop 0
	global_load_lds_dwordx4 v132, s[44:45]
	s_mov_b32 m0, s87
	s_nop 0
	global_load_lds_dwordx4 v136, s[44:45]
	s_waitcnt lgkmcnt(8)
	s_barrier
	s_waitcnt lgkmcnt(0)
	s_setprio 1
	s_waitcnt lgkmcnt(0)
	v_mfma_f32_16x16x32_bf16 v[128:131], v[140:143], v[156:159], v[128:131]
	v_mfma_f32_16x16x32_bf16 v[124:127], v[148:151], v[156:159], v[124:127]
	v_mfma_f32_16x16x32_bf16 v[112:115], v[140:143], v[164:167], v[112:115]
	v_mfma_f32_16x16x32_bf16 v[108:111], v[148:151], v[164:167], v[108:111]
	v_mfma_f32_16x16x32_bf16 v[96:99], v[140:143], v[172:175], v[96:99]
	v_mfma_f32_16x16x32_bf16 v[92:95], v[148:151], v[172:175], v[92:95]
	v_mfma_f32_16x16x32_bf16 v[80:83], v[140:143], v[180:183], v[80:83]
	v_mfma_f32_16x16x32_bf16 v[76:79], v[148:151], v[180:183], v[76:79]
	v_mfma_f32_16x16x32_bf16 v[128:131], v[144:147], v[160:163], v[128:131]
	v_mfma_f32_16x16x32_bf16 v[124:127], v[152:155], v[160:163], v[124:127]
	v_mfma_f32_16x16x32_bf16 v[112:115], v[144:147], v[168:171], v[112:115]
	v_mfma_f32_16x16x32_bf16 v[108:111], v[152:155], v[168:171], v[108:111]
	v_mfma_f32_16x16x32_bf16 v[96:99], v[144:147], v[176:179], v[96:99]
	v_mfma_f32_16x16x32_bf16 v[92:95], v[152:155], v[176:179], v[92:95]
	v_mfma_f32_16x16x32_bf16 v[80:83], v[144:147], v[184:187], v[80:83]
	v_mfma_f32_16x16x32_bf16 v[76:79], v[152:155], v[184:187], v[76:79]
	s_setprio 0
	s_barrier
	v_add_u32_e32 v214, s85, v1
	s_mov_b32 m0, s86
	ds_read_b128 v[188:191], v214
	ds_read_b128 v[192:195], v214 offset:1024
	ds_read_b128 v[210:213], v214 offset:2048
	ds_read_b128 v[214:217], v214 offset:3072
	s_nop 0
	global_load_lds_dwordx4 v134, s[42:43]
	s_mov_b32 m0, s84
	s_nop 0
	global_load_lds_dwordx4 v138, s[42:43]
	s_barrier
	s_waitcnt lgkmcnt(0)
	s_setprio 1
	s_waitcnt lgkmcnt(0)
	v_mfma_f32_16x16x32_bf16 v[120:123], v[188:191], v[156:159], v[120:123]
	v_mfma_f32_16x16x32_bf16 v[116:119], v[210:213], v[156:159], v[116:119]
	v_mfma_f32_16x16x32_bf16 v[104:107], v[188:191], v[164:167], v[104:107]
	v_mfma_f32_16x16x32_bf16 v[100:103], v[210:213], v[164:167], v[100:103]
	v_mfma_f32_16x16x32_bf16 v[88:91], v[188:191], v[172:175], v[88:91]
	v_mfma_f32_16x16x32_bf16 v[84:87], v[210:213], v[172:175], v[84:87]
	v_mfma_f32_16x16x32_bf16 v[72:75], v[188:191], v[180:183], v[72:75]
	v_mfma_f32_16x16x32_bf16 v[68:71], v[210:213], v[180:183], v[68:71]
	v_mfma_f32_16x16x32_bf16 v[120:123], v[192:195], v[160:163], v[120:123]
	v_mfma_f32_16x16x32_bf16 v[116:119], v[214:217], v[160:163], v[116:119]
	v_mfma_f32_16x16x32_bf16 v[104:107], v[192:195], v[168:171], v[104:107]
	v_mfma_f32_16x16x32_bf16 v[100:103], v[214:217], v[168:171], v[100:103]
	v_mfma_f32_16x16x32_bf16 v[88:91], v[192:195], v[176:179], v[88:91]
	v_mfma_f32_16x16x32_bf16 v[84:87], v[214:217], v[176:179], v[84:87]
	v_mfma_f32_16x16x32_bf16 v[72:75], v[192:195], v[184:187], v[72:75]
	v_mfma_f32_16x16x32_bf16 v[68:71], v[214:217], v[184:187], v[68:71]
	s_setprio 0
	s_mov_b32 m0, s52
	s_barrier
	ds_read_b128 v[156:159], v3 offset:16384
	ds_read_b128 v[160:163], v3 offset:17408
	ds_read_b128 v[164:167], v3 offset:18432
	ds_read_b128 v[168:171], v3 offset:19456
	ds_read_b128 v[172:175], v3 offset:20480
	ds_read_b128 v[176:179], v3 offset:21504
	ds_read_b128 v[180:183], v3 offset:22528
	ds_read_b128 v[184:187], v3 offset:23552
	s_nop 0
	global_load_lds_dwordx4 v132, s[40:41]
	s_mov_b32 m0, s53
	s_nop 0
	global_load_lds_dwordx4 v136, s[40:41]
	s_barrier
	s_waitcnt lgkmcnt(0)
	s_setprio 1
	s_waitcnt lgkmcnt(0)
	v_mfma_f32_16x16x32_bf16 v[64:67], v[140:143], v[156:159], v[64:67]
	v_mfma_f32_16x16x32_bf16 v[60:63], v[148:151], v[156:159], v[60:63]
	v_mfma_f32_16x16x32_bf16 v[48:51], v[140:143], v[164:167], v[48:51]
	v_mfma_f32_16x16x32_bf16 v[44:47], v[148:151], v[164:167], v[44:47]
	v_mfma_f32_16x16x32_bf16 v[32:35], v[140:143], v[172:175], v[32:35]
	v_mfma_f32_16x16x32_bf16 v[28:31], v[148:151], v[172:175], v[28:31]
	v_mfma_f32_16x16x32_bf16 v[16:19], v[140:143], v[180:183], v[16:19]
	v_mfma_f32_16x16x32_bf16 v[12:15], v[148:151], v[180:183], v[12:15]
	v_mfma_f32_16x16x32_bf16 v[64:67], v[144:147], v[160:163], v[64:67]
	v_mfma_f32_16x16x32_bf16 v[60:63], v[152:155], v[160:163], v[60:63]
	v_mfma_f32_16x16x32_bf16 v[48:51], v[144:147], v[168:171], v[48:51]
	v_mfma_f32_16x16x32_bf16 v[44:47], v[152:155], v[168:171], v[44:47]
	v_mfma_f32_16x16x32_bf16 v[32:35], v[144:147], v[176:179], v[32:35]
	v_mfma_f32_16x16x32_bf16 v[28:31], v[152:155], v[176:179], v[28:31]
	v_mfma_f32_16x16x32_bf16 v[16:19], v[144:147], v[184:187], v[16:19]
	v_mfma_f32_16x16x32_bf16 v[12:15], v[152:155], v[184:187], v[12:15]
	s_setprio 0
	s_barrier
	s_mov_b32 m0, s82
	s_nop 0
	global_load_lds_dwordx4 v134, s[38:39]
	s_mov_b32 m0, s80
	s_nop 0
	global_load_lds_dwordx4 v138, s[38:39]
	s_waitcnt vmcnt(6)
	s_barrier
	s_setprio 1
	v_mfma_f32_16x16x32_bf16 v[56:59], v[188:191], v[156:159], v[56:59]
	v_mfma_f32_16x16x32_bf16 v[52:55], v[210:213], v[156:159], v[52:55]
	v_mfma_f32_16x16x32_bf16 v[40:43], v[188:191], v[164:167], v[40:43]
	v_mfma_f32_16x16x32_bf16 v[36:39], v[210:213], v[164:167], v[36:39]
	v_mfma_f32_16x16x32_bf16 v[24:27], v[188:191], v[172:175], v[24:27]
	v_mfma_f32_16x16x32_bf16 v[20:23], v[210:213], v[172:175], v[20:23]
	v_mfma_f32_16x16x32_bf16 v[8:11], v[188:191], v[180:183], v[8:11]
	v_mfma_f32_16x16x32_bf16 v[4:7], v[210:213], v[180:183], v[4:7]
	v_mfma_f32_16x16x32_bf16 v[56:59], v[192:195], v[160:163], v[56:59]
	v_mfma_f32_16x16x32_bf16 v[52:55], v[214:217], v[160:163], v[52:55]
	v_mfma_f32_16x16x32_bf16 v[40:43], v[192:195], v[168:171], v[40:43]
	v_mfma_f32_16x16x32_bf16 v[36:39], v[214:217], v[168:171], v[36:39]
	v_mfma_f32_16x16x32_bf16 v[24:27], v[192:195], v[176:179], v[24:27]
	v_mfma_f32_16x16x32_bf16 v[20:23], v[214:217], v[176:179], v[20:23]
	v_mfma_f32_16x16x32_bf16 v[8:11], v[192:195], v[184:187], v[8:11]
	v_mfma_f32_16x16x32_bf16 v[4:7], v[214:217], v[184:187], v[4:7]
	s_setprio 0
	v_add_u32_e32 v152, s79, v1
	s_barrier
	ds_read_b128 v[140:143], v152
	ds_read_b128 v[144:147], v152 offset:1024
	ds_read_b128 v[148:151], v152 offset:2048
	ds_read_b128 v[152:155], v152 offset:3072
	s_mov_b32 m0, s55
	ds_read_b128 v[156:159], v3 offset:32768
	ds_read_b128 v[160:163], v3 offset:33792
	ds_read_b128 v[164:167], v3 offset:34816
	ds_read_b128 v[168:171], v3 offset:35840
	ds_read_b128 v[172:175], v3 offset:36864
	ds_read_b128 v[176:179], v3 offset:37888
	ds_read_b128 v[180:183], v3 offset:38912
	ds_read_b128 v[184:187], v3 offset:39936
	s_nop 0
	global_load_lds_dwordx4 v132, s[36:37]
	s_mov_b32 m0, s56
	s_nop 0
	global_load_lds_dwordx4 v136, s[36:37]
	s_waitcnt lgkmcnt(8)
	s_barrier
	s_waitcnt lgkmcnt(0)
	s_setprio 1
	s_waitcnt lgkmcnt(0)
	v_mfma_f32_16x16x32_bf16 v[128:131], v[140:143], v[156:159], v[128:131]
	v_mfma_f32_16x16x32_bf16 v[124:127], v[148:151], v[156:159], v[124:127]
	v_mfma_f32_16x16x32_bf16 v[112:115], v[140:143], v[164:167], v[112:115]
	v_mfma_f32_16x16x32_bf16 v[108:111], v[148:151], v[164:167], v[108:111]
	v_mfma_f32_16x16x32_bf16 v[96:99], v[140:143], v[172:175], v[96:99]
	v_mfma_f32_16x16x32_bf16 v[92:95], v[148:151], v[172:175], v[92:95]
	v_mfma_f32_16x16x32_bf16 v[80:83], v[140:143], v[180:183], v[80:83]
	v_mfma_f32_16x16x32_bf16 v[76:79], v[148:151], v[180:183], v[76:79]
	v_mfma_f32_16x16x32_bf16 v[128:131], v[144:147], v[160:163], v[128:131]
	v_mfma_f32_16x16x32_bf16 v[124:127], v[152:155], v[160:163], v[124:127]
	v_mfma_f32_16x16x32_bf16 v[112:115], v[144:147], v[168:171], v[112:115]
	v_mfma_f32_16x16x32_bf16 v[108:111], v[152:155], v[168:171], v[108:111]
	v_mfma_f32_16x16x32_bf16 v[96:99], v[144:147], v[176:179], v[96:99]
	v_mfma_f32_16x16x32_bf16 v[92:95], v[152:155], v[176:179], v[92:95]
	v_mfma_f32_16x16x32_bf16 v[80:83], v[144:147], v[184:187], v[80:83]
	v_mfma_f32_16x16x32_bf16 v[76:79], v[152:155], v[184:187], v[76:79]
	s_setprio 0
	s_barrier
	v_add_u32_e32 v214, s75, v1
	s_mov_b32 m0, s78
	ds_read_b128 v[188:191], v214
	ds_read_b128 v[192:195], v214 offset:1024
	ds_read_b128 v[210:213], v214 offset:2048
	ds_read_b128 v[214:217], v214 offset:3072
	s_nop 0
	global_load_lds_dwordx4 v134, s[30:31]
	s_mov_b32 m0, s74
	s_nop 0
	global_load_lds_dwordx4 v138, s[30:31]
	s_barrier
	s_waitcnt lgkmcnt(0)
	s_setprio 1
	s_waitcnt lgkmcnt(0)
	v_mfma_f32_16x16x32_bf16 v[120:123], v[188:191], v[156:159], v[120:123]
	v_mfma_f32_16x16x32_bf16 v[116:119], v[210:213], v[156:159], v[116:119]
	v_mfma_f32_16x16x32_bf16 v[104:107], v[188:191], v[164:167], v[104:107]
	v_mfma_f32_16x16x32_bf16 v[100:103], v[210:213], v[164:167], v[100:103]
	v_mfma_f32_16x16x32_bf16 v[88:91], v[188:191], v[172:175], v[88:91]
	v_mfma_f32_16x16x32_bf16 v[84:87], v[210:213], v[172:175], v[84:87]
	v_mfma_f32_16x16x32_bf16 v[72:75], v[188:191], v[180:183], v[72:75]
	v_mfma_f32_16x16x32_bf16 v[68:71], v[210:213], v[180:183], v[68:71]
	v_mfma_f32_16x16x32_bf16 v[120:123], v[192:195], v[160:163], v[120:123]
	v_mfma_f32_16x16x32_bf16 v[116:119], v[214:217], v[160:163], v[116:119]
	v_mfma_f32_16x16x32_bf16 v[104:107], v[192:195], v[168:171], v[104:107]
	v_mfma_f32_16x16x32_bf16 v[100:103], v[214:217], v[168:171], v[100:103]
	v_mfma_f32_16x16x32_bf16 v[88:91], v[192:195], v[176:179], v[88:91]
	v_mfma_f32_16x16x32_bf16 v[84:87], v[214:217], v[176:179], v[84:87]
	v_mfma_f32_16x16x32_bf16 v[72:75], v[192:195], v[184:187], v[72:75]
	v_mfma_f32_16x16x32_bf16 v[68:71], v[214:217], v[184:187], v[68:71]
	s_setprio 0
	s_mov_b32 m0, s65
	s_barrier
	ds_read_b128 v[156:159], v3 offset:49152
	ds_read_b128 v[160:163], v3 offset:50176
	ds_read_b128 v[164:167], v3 offset:51200
	ds_read_b128 v[168:171], v3 offset:52224
	ds_read_b128 v[172:175], v3 offset:53248
	ds_read_b128 v[176:179], v3 offset:54272
	ds_read_b128 v[180:183], v3 offset:55296
	ds_read_b128 v[184:187], v3 offset:56320
	s_nop 0
	global_load_lds_dwordx4 v132, s[26:27]
	s_mov_b32 m0, s67
	s_nop 0
	global_load_lds_dwordx4 v136, s[26:27]
	s_barrier
	s_waitcnt lgkmcnt(0)
	s_setprio 1
	s_waitcnt lgkmcnt(0)
	v_mfma_f32_16x16x32_bf16 v[64:67], v[140:143], v[156:159], v[64:67]
	v_mfma_f32_16x16x32_bf16 v[60:63], v[148:151], v[156:159], v[60:63]
	v_mfma_f32_16x16x32_bf16 v[48:51], v[140:143], v[164:167], v[48:51]
	v_mfma_f32_16x16x32_bf16 v[44:47], v[148:151], v[164:167], v[44:47]
	v_mfma_f32_16x16x32_bf16 v[32:35], v[140:143], v[172:175], v[32:35]
	v_mfma_f32_16x16x32_bf16 v[28:31], v[148:151], v[172:175], v[28:31]
	v_mfma_f32_16x16x32_bf16 v[16:19], v[140:143], v[180:183], v[16:19]
	v_mfma_f32_16x16x32_bf16 v[12:15], v[148:151], v[180:183], v[12:15]
	v_mfma_f32_16x16x32_bf16 v[64:67], v[144:147], v[160:163], v[64:67]
	v_mfma_f32_16x16x32_bf16 v[60:63], v[152:155], v[160:163], v[60:63]
	v_mfma_f32_16x16x32_bf16 v[48:51], v[144:147], v[168:171], v[48:51]
	v_mfma_f32_16x16x32_bf16 v[44:47], v[152:155], v[168:171], v[44:47]
	v_mfma_f32_16x16x32_bf16 v[32:35], v[144:147], v[176:179], v[32:35]
	v_mfma_f32_16x16x32_bf16 v[28:31], v[152:155], v[176:179], v[28:31]
	v_mfma_f32_16x16x32_bf16 v[16:19], v[144:147], v[184:187], v[16:19]
	v_mfma_f32_16x16x32_bf16 v[12:15], v[152:155], v[184:187], v[12:15]
	s_setprio 0
	s_barrier
	s_mov_b32 m0, s83
	s_nop 0
	global_load_lds_dwordx4 v134, s[28:29]
	s_mov_b32 m0, s81
	s_nop 0
	global_load_lds_dwordx4 v138, s[28:29]
	s_waitcnt vmcnt(6)
	s_barrier
	s_setprio 1
	v_mfma_f32_16x16x32_bf16 v[56:59], v[188:191], v[156:159], v[56:59]
	v_mfma_f32_16x16x32_bf16 v[52:55], v[210:213], v[156:159], v[52:55]
	v_mfma_f32_16x16x32_bf16 v[40:43], v[188:191], v[164:167], v[40:43]
	v_mfma_f32_16x16x32_bf16 v[36:39], v[210:213], v[164:167], v[36:39]
	v_mfma_f32_16x16x32_bf16 v[24:27], v[188:191], v[172:175], v[24:27]
	v_mfma_f32_16x16x32_bf16 v[20:23], v[210:213], v[172:175], v[20:23]
	v_mfma_f32_16x16x32_bf16 v[8:11], v[188:191], v[180:183], v[8:11]
	v_mfma_f32_16x16x32_bf16 v[4:7], v[210:213], v[180:183], v[4:7]
	v_mfma_f32_16x16x32_bf16 v[56:59], v[192:195], v[160:163], v[56:59]
	v_mfma_f32_16x16x32_bf16 v[52:55], v[214:217], v[160:163], v[52:55]
	v_mfma_f32_16x16x32_bf16 v[40:43], v[192:195], v[168:171], v[40:43]
	v_mfma_f32_16x16x32_bf16 v[36:39], v[214:217], v[168:171], v[36:39]
	v_mfma_f32_16x16x32_bf16 v[24:27], v[192:195], v[176:179], v[24:27]
	v_mfma_f32_16x16x32_bf16 v[20:23], v[214:217], v[176:179], v[20:23]
	v_mfma_f32_16x16x32_bf16 v[8:11], v[192:195], v[184:187], v[8:11]
	v_mfma_f32_16x16x32_bf16 v[4:7], v[214:217], v[184:187], v[4:7]
	s_setprio 0
	s_andn2_b64 vcc, exec, s[24:25]
	s_mov_b64 s[28:29], -1
	s_mov_b64 s[24:25], 0
	s_mov_b64 s[26:27], 0x100
	s_barrier
	s_cbranch_vccz .LBB0_654
	v_mov_b32_e32 v141, v0
	s_ashr_i32 s23, s22, 31
	v_readfirstlane_b32 s0, v141
	s_bfe_u32 s17, s0, 0x20006
	s_ashr_i32 s0, s0, 2
	s_andn2_b32 s0, s0, 63
	s_ashr_i32 s1, s0, 31
	s_lshl_b64 s[14:15], s[22:23], 10
	s_add_u32 s24, s57, s14
	s_addc_u32 s25, s62, s15
	s_lshl_b64 s[14:15], s[0:1], 2
	v_and_b32_e32 v142, 15, v141
	s_add_u32 s24, s24, s14
	s_addc_u32 s25, s25, s15
	v_lshlrev_b32_e32 v140, 2, v142
	s_min_u32 s100, s72, 0x7ff
	s_lshl_b32 s100, s100, 10
	v_and_b32_e32 v210, 7, v0
	v_lshlrev_b32_e32 v210, 7, v210
	v_add_u32_e32 v210, s100, v210
	s_mov_b32 s100, s57
	s_mov_b32 s101, s62
	global_load_dword v211, v210, s[100:101]
	global_load_dword v150, v140, s[24:25] offset:64
	global_load_dword v149, v140, s[24:25] offset:128
	global_load_dword v148, v140, s[24:25] offset:192
	global_load_dword v147, v140, s[24:25] offset:512
	global_load_dword v146, v140, s[24:25] offset:576
	global_load_dword v145, v140, s[24:25] offset:640
	global_load_dword v144, v140, s[24:25] offset:704
	v_mul_f32_e32 v129, v129, v129
	v_mul_f32_e32 v125, v125, v125
	v_mul_f32_e32 v121, v121, v121
	v_mul_f32_e32 v117, v117, v117
	v_fmac_f32_e32 v129, v128, v128
	v_mul_f32_e32 v128, v131, v131
	v_fmac_f32_e32 v125, v124, v124
	v_mul_f32_e32 v124, v127, v127
	v_fmac_f32_e32 v121, v120, v120
	v_mul_f32_e32 v120, v123, v123
	v_fmac_f32_e32 v117, v116, v116
	v_mul_f32_e32 v116, v119, v119
	v_fmac_f32_e32 v128, v130, v130
	v_fmac_f32_e32 v124, v126, v126
	v_fmac_f32_e32 v120, v122, v122
	v_fmac_f32_e32 v116, v118, v118
	v_add_f32_e32 v128, v129, v128
	v_add_f32_e32 v124, v125, v124
	v_add_f32_e32 v120, v121, v120
	v_add_f32_e32 v116, v117, v116
	v_add_f32_e32 v124, v128, v124
	v_add_f32_e32 v116, v120, v116
	v_add_f32_e32 v117, v124, v116
	v_mov_b32_e32 v118, v117
	s_nop 1
	v_permlane16_swap_b32 v118, v117
	v_and_b32_e32 v152, 64, v236
	v_xor_b32_e32 v151, 32, v236
	v_add_u32_e32 v152, 64, v152
	v_cmp_lt_i32_e32 vcc, v151, v152
	s_lshl_b32 s14, s73, 2
	s_or_b32 s26, s17, s14
	v_cndmask_b32_e32 v116, v236, v151, vcc
	s_lshl_b64 s[14:15], s[22:23], 8
	v_lshlrev_b32_e32 v116, 2, v116
	s_waitcnt lgkmcnt(0)
	v_add_f32_e32 v117, v117, v118
	s_add_u32 s0, s14, s0
	v_mov_b32_e32 v118, v117
	s_nop 1
	v_permlane32_swap_b32 v118, v117
	s_addc_u32 s1, s15, s1
	s_ashr_i32 s27, s26, 31
	v_or_b32_e32 v143, s0, v142
	v_mov_b32_e32 v142, s1
	s_lshl_b64 s[0:1], s[26:27], 2
	v_and_b32_e32 v119, 48, v141
	s_add_u32 s0, s63, s0
	v_cmp_eq_u32_e64 s[14:15], 0, v119
	s_addc_u32 s1, s64, s1
	s_and_saveexec_b64 s[22:23], s[14:15]
	s_cbranch_execz .LBB0_657
	v_mov_b32_e32 v141, v2
	v_lshl_add_u64 v[120:121], s[24:25], 0, v[140:141]
	global_load_dword v119, v[120:121], off
	s_waitcnt lgkmcnt(0)
	v_add_f32_e32 v117, v117, v118
	s_waitcnt vmcnt(0)
	v_add_f32_e32 v117, v117, v119
	v_fmamk_f32 v117, v117, 0x3c2aaaab, v231
	v_cmp_gt_f32_e32 vcc, s11, v117
	v_mul_f32_e32 v118, 0x4b800000, v117
	s_nop 0
	v_cndmask_b32_e32 v117, v117, v118, vcc
	v_rsq_f32_e32 v117, v117
	s_nop 0
	v_mul_f32_e32 v118, 0x45800000, v117
	v_cndmask_b32_e32 v117, v117, v118, vcc
	v_mad_u64_u32 v[118:119], s[24:25], v143, 48, s[0:1]
	v_mov_b32_e32 v120, v119
	v_mad_u64_u32 v[120:121], s[24:25], v142, 48, v[120:121]
	v_mov_b32_e32 v119, v120
	global_store_dword v[118:119], v117, off

.LBB0_2213:
	s_add_u32 s15, s20, s24
	s_addc_u32 s30, s21, s25
	s_add_u32 s31, s15, 0x100
	s_addc_u32 s38, s30, 0
	s_and_b64 s[28:29], s[26:27], exec
	s_cselect_b32 s41, s9, s38
	s_cselect_b32 s40, s8, s31
	s_add_u32 s24, s16, s24
	s_addc_u32 s25, s17, s25
	s_add_u32 s28, s24, 0x100
	s_addc_u32 s29, s25, 0
	s_add_u32 s24, s40, 0x80
	s_addc_u32 s25, s41, 0
	s_add_i32 s79, 0, 0x10000
	s_and_b64 s[26:27], s[26:27], exec
	s_cselect_b32 s43, s1, s29
	s_cselect_b32 s42, s7, s28
	s_add_u32 s44, s15, 0x12080
	s_addc_u32 s45, s30, 0
	s_add_i32 s84, s79, s51
	s_add_i32 m0, s52, 0xc000
	s_add_i32 s85, s52, 0xe000
	s_add_i32 s83, 0, 0x14000
	s_add_i32 s82, s84, 0x2000
	s_add_u32 s38, s42, 0x10000
	s_addc_u32 s39, s43, 0
	s_add_i32 s80, s83, s51
	s_add_i32 s78, s80, 0x2000
	s_add_i32 s75, 0, 0x18000
	v_add_u32_e32 v152, s79, v1
	s_add_u32 s30, s40, 0x12000
	ds_read_b128 v[140:143], v152
	ds_read_b128 v[144:147], v152 offset:1024
	ds_read_b128 v[148:151], v152 offset:2048
	ds_read_b128 v[152:155], v152 offset:3072
	s_addc_u32 s31, s41, 0
	s_add_i32 s73, 0, 0x1c000
	s_add_u32 s28, s42, 0x80
	s_addc_u32 s29, s43, 0
	s_add_i32 s74, s75, s51
	s_add_i32 s15, s74, 0x2000
	s_add_u32 s26, s42, 0x10080
	s_addc_u32 s27, s43, 0
	s_add_i32 s81, s73, s51
	s_add_i32 s79, s81, 0x2000
	ds_read_b128 v[156:159], v3
	ds_read_b128 v[160:163], v3 offset:1024
	ds_read_b128 v[164:167], v3 offset:2048
	ds_read_b128 v[168:171], v3 offset:3072
	ds_read_b128 v[172:175], v3 offset:4096
	ds_read_b128 v[176:179], v3 offset:5120
	ds_read_b128 v[180:183], v3 offset:6144
	ds_read_b128 v[184:187], v3 offset:7168
	s_nop 0
	global_load_lds_dwordx4 v132, s[44:45]
	s_mov_b32 m0, s85
	s_nop 0
	global_load_lds_dwordx4 v136, s[44:45]
	s_waitcnt lgkmcnt(8)
	s_barrier
	s_waitcnt lgkmcnt(0)
	s_setprio 1
	s_waitcnt lgkmcnt(0)
	v_mfma_f32_16x16x32_bf16 v[128:131], v[140:143], v[156:159], v[128:131]
	v_mfma_f32_16x16x32_bf16 v[124:127], v[148:151], v[156:159], v[124:127]
	v_mfma_f32_16x16x32_bf16 v[112:115], v[140:143], v[164:167], v[112:115]
	v_mfma_f32_16x16x32_bf16 v[108:111], v[148:151], v[164:167], v[108:111]
	v_mfma_f32_16x16x32_bf16 v[96:99], v[140:143], v[172:175], v[96:99]
	v_mfma_f32_16x16x32_bf16 v[92:95], v[148:151], v[172:175], v[92:95]
	v_mfma_f32_16x16x32_bf16 v[80:83], v[140:143], v[180:183], v[80:83]
	v_mfma_f32_16x16x32_bf16 v[76:79], v[148:151], v[180:183], v[76:79]
	v_mfma_f32_16x16x32_bf16 v[128:131], v[144:147], v[160:163], v[128:131]
	v_mfma_f32_16x16x32_bf16 v[124:127], v[152:155], v[160:163], v[124:127]
	v_mfma_f32_16x16x32_bf16 v[112:115], v[144:147], v[168:171], v[112:115]
	v_mfma_f32_16x16x32_bf16 v[108:111], v[152:155], v[168:171], v[108:111]
	v_mfma_f32_16x16x32_bf16 v[96:99], v[144:147], v[176:179], v[96:99]
	v_mfma_f32_16x16x32_bf16 v[92:95], v[152:155], v[176:179], v[92:95]
	v_mfma_f32_16x16x32_bf16 v[80:83], v[144:147], v[184:187], v[80:83]
	v_mfma_f32_16x16x32_bf16 v[76:79], v[152:155], v[184:187], v[76:79]
	s_setprio 0
	s_barrier
	v_add_u32_e32 v214, s83, v1
	s_mov_b32 m0, s84
	ds_read_b128 v[188:191], v214
	ds_read_b128 v[192:195], v214 offset:1024
	ds_read_b128 v[210:213], v214 offset:2048
	ds_read_b128 v[214:217], v214 offset:3072
	s_nop 0
	global_load_lds_dwordx4 v134, s[42:43]
	s_mov_b32 m0, s82
	s_nop 0
	global_load_lds_dwordx4 v138, s[42:43]
	s_barrier
	s_waitcnt lgkmcnt(0)
	s_setprio 1
	s_waitcnt lgkmcnt(0)
	v_mfma_f32_16x16x32_bf16 v[120:123], v[188:191], v[156:159], v[120:123]
	v_mfma_f32_16x16x32_bf16 v[116:119], v[210:213], v[156:159], v[116:119]
	v_mfma_f32_16x16x32_bf16 v[104:107], v[188:191], v[164:167], v[104:107]
	v_mfma_f32_16x16x32_bf16 v[100:103], v[210:213], v[164:167], v[100:103]
	v_mfma_f32_16x16x32_bf16 v[88:91], v[188:191], v[172:175], v[88:91]
	v_mfma_f32_16x16x32_bf16 v[84:87], v[210:213], v[172:175], v[84:87]
	v_mfma_f32_16x16x32_bf16 v[72:75], v[188:191], v[180:183], v[72:75]
	v_mfma_f32_16x16x32_bf16 v[68:71], v[210:213], v[180:183], v[68:71]
	v_mfma_f32_16x16x32_bf16 v[120:123], v[192:195], v[160:163], v[120:123]
	v_mfma_f32_16x16x32_bf16 v[116:119], v[214:217], v[160:163], v[116:119]
	v_mfma_f32_16x16x32_bf16 v[104:107], v[192:195], v[168:171], v[104:107]
	v_mfma_f32_16x16x32_bf16 v[100:103], v[214:217], v[168:171], v[100:103]
	v_mfma_f32_16x16x32_bf16 v[88:91], v[192:195], v[176:179], v[88:91]
	v_mfma_f32_16x16x32_bf16 v[84:87], v[214:217], v[176:179], v[84:87]
	v_mfma_f32_16x16x32_bf16 v[72:75], v[192:195], v[184:187], v[72:75]
	v_mfma_f32_16x16x32_bf16 v[68:71], v[214:217], v[184:187], v[68:71]
	s_setprio 0
	s_mov_b32 m0, s52
	s_barrier
	ds_read_b128 v[156:159], v3 offset:16384
	ds_read_b128 v[160:163], v3 offset:17408
	ds_read_b128 v[164:167], v3 offset:18432
	ds_read_b128 v[168:171], v3 offset:19456
	ds_read_b128 v[172:175], v3 offset:20480
	ds_read_b128 v[176:179], v3 offset:21504
	ds_read_b128 v[180:183], v3 offset:22528
	ds_read_b128 v[184:187], v3 offset:23552
	s_nop 0
	global_load_lds_dwordx4 v132, s[40:41]
	s_mov_b32 m0, s53
	s_nop 0
	global_load_lds_dwordx4 v136, s[40:41]
	s_barrier
	s_waitcnt lgkmcnt(0)
	s_setprio 1
	s_waitcnt lgkmcnt(0)
	v_mfma_f32_16x16x32_bf16 v[64:67], v[140:143], v[156:159], v[64:67]
	v_mfma_f32_16x16x32_bf16 v[60:63], v[148:151], v[156:159], v[60:63]
	v_mfma_f32_16x16x32_bf16 v[48:51], v[140:143], v[164:167], v[48:51]
	v_mfma_f32_16x16x32_bf16 v[44:47], v[148:151], v[164:167], v[44:47]
	v_mfma_f32_16x16x32_bf16 v[32:35], v[140:143], v[172:175], v[32:35]
	v_mfma_f32_16x16x32_bf16 v[28:31], v[148:151], v[172:175], v[28:31]
	v_mfma_f32_16x16x32_bf16 v[16:19], v[140:143], v[180:183], v[16:19]
	v_mfma_f32_16x16x32_bf16 v[12:15], v[148:151], v[180:183], v[12:15]
	v_mfma_f32_16x16x32_bf16 v[64:67], v[144:147], v[160:163], v[64:67]
	v_mfma_f32_16x16x32_bf16 v[60:63], v[152:155], v[160:163], v[60:63]
	v_mfma_f32_16x16x32_bf16 v[48:51], v[144:147], v[168:171], v[48:51]
	v_mfma_f32_16x16x32_bf16 v[44:47], v[152:155], v[168:171], v[44:47]
	v_mfma_f32_16x16x32_bf16 v[32:35], v[144:147], v[176:179], v[32:35]
	v_mfma_f32_16x16x32_bf16 v[28:31], v[152:155], v[176:179], v[28:31]
	v_mfma_f32_16x16x32_bf16 v[16:19], v[144:147], v[184:187], v[16:19]
	v_mfma_f32_16x16x32_bf16 v[12:15], v[152:155], v[184:187], v[12:15]
	s_setprio 0
	s_barrier
	s_mov_b32 m0, s80
	s_nop 0
	global_load_lds_dwordx4 v134, s[38:39]
	s_mov_b32 m0, s78
	s_nop 0
	global_load_lds_dwordx4 v138, s[38:39]
	s_waitcnt vmcnt(6)
	s_barrier
	s_setprio 1
	v_mfma_f32_16x16x32_bf16 v[56:59], v[188:191], v[156:159], v[56:59]
	v_mfma_f32_16x16x32_bf16 v[52:55], v[210:213], v[156:159], v[52:55]
	v_mfma_f32_16x16x32_bf16 v[40:43], v[188:191], v[164:167], v[40:43]
	v_mfma_f32_16x16x32_bf16 v[36:39], v[210:213], v[164:167], v[36:39]
	v_mfma_f32_16x16x32_bf16 v[24:27], v[188:191], v[172:175], v[24:27]
	v_mfma_f32_16x16x32_bf16 v[20:23], v[210:213], v[172:175], v[20:23]
	v_mfma_f32_16x16x32_bf16 v[8:11], v[188:191], v[180:183], v[8:11]
	v_mfma_f32_16x16x32_bf16 v[4:7], v[210:213], v[180:183], v[4:7]
	v_mfma_f32_16x16x32_bf16 v[56:59], v[192:195], v[160:163], v[56:59]
	v_mfma_f32_16x16x32_bf16 v[52:55], v[214:217], v[160:163], v[52:55]
	v_mfma_f32_16x16x32_bf16 v[40:43], v[192:195], v[168:171], v[40:43]
	v_mfma_f32_16x16x32_bf16 v[36:39], v[214:217], v[168:171], v[36:39]
	v_mfma_f32_16x16x32_bf16 v[24:27], v[192:195], v[176:179], v[24:27]
	v_mfma_f32_16x16x32_bf16 v[20:23], v[214:217], v[176:179], v[20:23]
	v_mfma_f32_16x16x32_bf16 v[8:11], v[192:195], v[184:187], v[8:11]
	v_mfma_f32_16x16x32_bf16 v[4:7], v[214:217], v[184:187], v[4:7]
	s_setprio 0
	v_add_u32_e32 v152, s75, v1
	s_barrier
	ds_read_b128 v[140:143], v152
	ds_read_b128 v[144:147], v152 offset:1024
	ds_read_b128 v[148:151], v152 offset:2048
	ds_read_b128 v[152:155], v152 offset:3072
	s_mov_b32 m0, s54
	ds_read_b128 v[156:159], v3 offset:32768
	ds_read_b128 v[160:163], v3 offset:33792
	ds_read_b128 v[164:167], v3 offset:34816
	ds_read_b128 v[168:171], v3 offset:35840
	ds_read_b128 v[172:175], v3 offset:36864
	ds_read_b128 v[176:179], v3 offset:37888
	ds_read_b128 v[180:183], v3 offset:38912
	ds_read_b128 v[184:187], v3 offset:39936
	s_nop 0
	global_load_lds_dwordx4 v132, s[30:31]
	s_mov_b32 m0, s55
	s_nop 0
	global_load_lds_dwordx4 v136, s[30:31]
	s_waitcnt lgkmcnt(8)
	s_barrier
	s_waitcnt lgkmcnt(0)
	s_setprio 1
	s_waitcnt lgkmcnt(0)
	v_mfma_f32_16x16x32_bf16 v[128:131], v[140:143], v[156:159], v[128:131]
	v_mfma_f32_16x16x32_bf16 v[124:127], v[148:151], v[156:159], v[124:127]
	v_mfma_f32_16x16x32_bf16 v[112:115], v[140:143], v[164:167], v[112:115]
	v_mfma_f32_16x16x32_bf16 v[108:111], v[148:151], v[164:167], v[108:111]
	v_mfma_f32_16x16x32_bf16 v[96:99], v[140:143], v[172:175], v[96:99]
	v_mfma_f32_16x16x32_bf16 v[92:95], v[148:151], v[172:175], v[92:95]
	v_mfma_f32_16x16x32_bf16 v[80:83], v[140:143], v[180:183], v[80:83]
	v_mfma_f32_16x16x32_bf16 v[76:79], v[148:151], v[180:183], v[76:79]
	v_mfma_f32_16x16x32_bf16 v[128:131], v[144:147], v[160:163], v[128:131]
	v_mfma_f32_16x16x32_bf16 v[124:127], v[152:155], v[160:163], v[124:127]
	v_mfma_f32_16x16x32_bf16 v[112:115], v[144:147], v[168:171], v[112:115]
	v_mfma_f32_16x16x32_bf16 v[108:111], v[152:155], v[168:171], v[108:111]
	v_mfma_f32_16x16x32_bf16 v[96:99], v[144:147], v[176:179], v[96:99]
	v_mfma_f32_16x16x32_bf16 v[92:95], v[152:155], v[176:179], v[92:95]
	v_mfma_f32_16x16x32_bf16 v[80:83], v[144:147], v[184:187], v[80:83]
	v_mfma_f32_16x16x32_bf16 v[76:79], v[152:155], v[184:187], v[76:79]
	s_setprio 0
	s_barrier
	v_add_u32_e32 v214, s73, v1
	s_mov_b32 m0, s74
	ds_read_b128 v[188:191], v214
	ds_read_b128 v[192:195], v214 offset:1024
	ds_read_b128 v[210:213], v214 offset:2048
	ds_read_b128 v[214:217], v214 offset:3072
	s_nop 0
	global_load_lds_dwordx4 v134, s[28:29]
	s_mov_b32 m0, s15
	s_nop 0
	global_load_lds_dwordx4 v138, s[28:29]
	s_barrier
	s_waitcnt lgkmcnt(0)
	s_setprio 1
	s_waitcnt lgkmcnt(0)
	v_mfma_f32_16x16x32_bf16 v[120:123], v[188:191], v[156:159], v[120:123]
	v_mfma_f32_16x16x32_bf16 v[116:119], v[210:213], v[156:159], v[116:119]
	v_mfma_f32_16x16x32_bf16 v[104:107], v[188:191], v[164:167], v[104:107]
	v_mfma_f32_16x16x32_bf16 v[100:103], v[210:213], v[164:167], v[100:103]
	v_mfma_f32_16x16x32_bf16 v[88:91], v[188:191], v[172:175], v[88:91]
	v_mfma_f32_16x16x32_bf16 v[84:87], v[210:213], v[172:175], v[84:87]
	v_mfma_f32_16x16x32_bf16 v[72:75], v[188:191], v[180:183], v[72:75]
	v_mfma_f32_16x16x32_bf16 v[68:71], v[210:213], v[180:183], v[68:71]
	v_mfma_f32_16x16x32_bf16 v[120:123], v[192:195], v[160:163], v[120:123]
	v_mfma_f32_16x16x32_bf16 v[116:119], v[214:217], v[160:163], v[116:119]
	v_mfma_f32_16x16x32_bf16 v[104:107], v[192:195], v[168:171], v[104:107]
	v_mfma_f32_16x16x32_bf16 v[100:103], v[214:217], v[168:171], v[100:103]
	v_mfma_f32_16x16x32_bf16 v[88:91], v[192:195], v[176:179], v[88:91]
	v_mfma_f32_16x16x32_bf16 v[84:87], v[214:217], v[176:179], v[84:87]
	v_mfma_f32_16x16x32_bf16 v[72:75], v[192:195], v[184:187], v[72:75]
	v_mfma_f32_16x16x32_bf16 v[68:71], v[214:217], v[184:187], v[68:71]
	s_setprio 0
	s_mov_b32 m0, s64
	s_barrier
	ds_read_b128 v[156:159], v3 offset:49152
	ds_read_b128 v[160:163], v3 offset:50176
	ds_read_b128 v[164:167], v3 offset:51200
	ds_read_b128 v[168:171], v3 offset:52224
	ds_read_b128 v[172:175], v3 offset:53248
	ds_read_b128 v[176:179], v3 offset:54272
	ds_read_b128 v[180:183], v3 offset:55296
	ds_read_b128 v[184:187], v3 offset:56320
	s_nop 0
	global_load_lds_dwordx4 v132, s[24:25]
	s_mov_b32 m0, s65
	s_nop 0
	global_load_lds_dwordx4 v136, s[24:25]
	s_barrier
	s_waitcnt lgkmcnt(0)
	s_setprio 1
	s_waitcnt lgkmcnt(0)
	v_mfma_f32_16x16x32_bf16 v[64:67], v[140:143], v[156:159], v[64:67]
	v_mfma_f32_16x16x32_bf16 v[60:63], v[148:151], v[156:159], v[60:63]
	v_mfma_f32_16x16x32_bf16 v[48:51], v[140:143], v[164:167], v[48:51]
	v_mfma_f32_16x16x32_bf16 v[44:47], v[148:151], v[164:167], v[44:47]
	v_mfma_f32_16x16x32_bf16 v[32:35], v[140:143], v[172:175], v[32:35]
	v_mfma_f32_16x16x32_bf16 v[28:31], v[148:151], v[172:175], v[28:31]
	v_mfma_f32_16x16x32_bf16 v[16:19], v[140:143], v[180:183], v[16:19]
	v_mfma_f32_16x16x32_bf16 v[12:15], v[148:151], v[180:183], v[12:15]
	v_mfma_f32_16x16x32_bf16 v[64:67], v[144:147], v[160:163], v[64:67]
	v_mfma_f32_16x16x32_bf16 v[60:63], v[152:155], v[160:163], v[60:63]
	v_mfma_f32_16x16x32_bf16 v[48:51], v[144:147], v[168:171], v[48:51]
	v_mfma_f32_16x16x32_bf16 v[44:47], v[152:155], v[168:171], v[44:47]
	v_mfma_f32_16x16x32_bf16 v[32:35], v[144:147], v[176:179], v[32:35]
	v_mfma_f32_16x16x32_bf16 v[28:31], v[152:155], v[176:179], v[28:31]
	v_mfma_f32_16x16x32_bf16 v[16:19], v[144:147], v[184:187], v[16:19]
	v_mfma_f32_16x16x32_bf16 v[12:15], v[152:155], v[184:187], v[12:15]
	s_setprio 0
	s_barrier
	s_mov_b32 m0, s81
	s_nop 0
	global_load_lds_dwordx4 v134, s[26:27]
	s_mov_b32 m0, s79
	s_nop 0
	global_load_lds_dwordx4 v138, s[26:27]
	s_waitcnt vmcnt(6)
	s_barrier
	s_setprio 1
	v_mfma_f32_16x16x32_bf16 v[56:59], v[188:191], v[156:159], v[56:59]
	v_mfma_f32_16x16x32_bf16 v[52:55], v[210:213], v[156:159], v[52:55]
	v_mfma_f32_16x16x32_bf16 v[40:43], v[188:191], v[164:167], v[40:43]
	v_mfma_f32_16x16x32_bf16 v[36:39], v[210:213], v[164:167], v[36:39]
	v_mfma_f32_16x16x32_bf16 v[24:27], v[188:191], v[172:175], v[24:27]
	v_mfma_f32_16x16x32_bf16 v[20:23], v[210:213], v[172:175], v[20:23]
	v_mfma_f32_16x16x32_bf16 v[8:11], v[188:191], v[180:183], v[8:11]
	v_mfma_f32_16x16x32_bf16 v[4:7], v[210:213], v[180:183], v[4:7]
	v_mfma_f32_16x16x32_bf16 v[56:59], v[192:195], v[160:163], v[56:59]
	v_mfma_f32_16x16x32_bf16 v[52:55], v[214:217], v[160:163], v[52:55]
	v_mfma_f32_16x16x32_bf16 v[40:43], v[192:195], v[168:171], v[40:43]
	v_mfma_f32_16x16x32_bf16 v[36:39], v[214:217], v[168:171], v[36:39]
	v_mfma_f32_16x16x32_bf16 v[24:27], v[192:195], v[176:179], v[24:27]
	v_mfma_f32_16x16x32_bf16 v[20:23], v[214:217], v[176:179], v[20:23]
	v_mfma_f32_16x16x32_bf16 v[8:11], v[192:195], v[184:187], v[8:11]
	v_mfma_f32_16x16x32_bf16 v[4:7], v[214:217], v[184:187], v[4:7]
	s_setprio 0
	s_andn2_b64 vcc, exec, s[22:23]
	s_mov_b64 s[26:27], -1
	s_mov_b64 s[22:23], 0
	s_mov_b64 s[24:25], 0x100
	s_barrier
	s_cbranch_vccz .LBB0_2213
	v_mov_b32_e32 v141, v0
	s_ashr_i32 s15, s14, 31
	v_readfirstlane_b32 s1, v141
	s_bfe_u32 s7, s1, 0x20006
	s_ashr_i32 s1, s1, 2
	s_and_b32 s16, s1, 0xffffffc0
	s_ashr_i32 s17, s16, 31
	s_lshl_b64 s[20:21], s[14:15], 10
	s_add_u32 s1, s56, s20
	s_addc_u32 s22, s57, s21
	s_lshl_b64 s[20:21], s[16:17], 2
	v_and_b32_e32 v142, 15, v141
	s_add_u32 s20, s1, s20
	s_addc_u32 s21, s22, s21
	v_lshlrev_b32_e32 v140, 2, v142
	s_min_u32 s100, s72, 0x7ff
	s_lshl_b32 s100, s100, 10
	v_and_b32_e32 v210, 7, v0
	v_lshlrev_b32_e32 v210, 7, v210
	v_add_u32_e32 v210, s100, v210
	global_load_dword v211, v210, s[56:57]
	global_load_dword v150, v140, s[20:21] offset:64
	global_load_dword v149, v140, s[20:21] offset:128
	global_load_dword v148, v140, s[20:21] offset:192
	global_load_dword v147, v140, s[20:21] offset:512
	global_load_dword v146, v140, s[20:21] offset:576
	global_load_dword v145, v140, s[20:21] offset:640
	global_load_dword v144, v140, s[20:21] offset:704
	v_mul_f32_e32 v129, v129, v129
	v_mul_f32_e32 v125, v125, v125
	v_mul_f32_e32 v121, v121, v121
	v_mul_f32_e32 v117, v117, v117
	v_fmac_f32_e32 v129, v128, v128
	v_mul_f32_e32 v128, v131, v131
	v_fmac_f32_e32 v125, v124, v124
	v_mul_f32_e32 v124, v127, v127
	v_fmac_f32_e32 v121, v120, v120
	v_mul_f32_e32 v120, v123, v123
	v_fmac_f32_e32 v117, v116, v116
	v_mul_f32_e32 v116, v119, v119
	v_fmac_f32_e32 v128, v130, v130
	v_fmac_f32_e32 v124, v126, v126
	v_fmac_f32_e32 v120, v122, v122
	v_fmac_f32_e32 v116, v118, v118
	v_add_f32_e32 v128, v129, v128
	v_add_f32_e32 v124, v125, v124
	v_add_f32_e32 v120, v121, v120
	v_add_f32_e32 v116, v117, v116
	v_add_f32_e32 v124, v128, v124
	v_add_f32_e32 v116, v120, v116
	v_add_f32_e32 v117, v124, v116
	v_mov_b32_e32 v118, v117
	s_nop 1
	v_permlane16_swap_b32 v118, v117
	v_and_b32_e32 v152, 64, v236
	v_xor_b32_e32 v151, 32, v236
	v_add_u32_e32 v152, 64, v152
	v_cmp_lt_i32_e32 vcc, v151, v152
	s_lshl_b32 s0, s0, 2
	s_or_b32 s0, s7, s0
	v_cndmask_b32_e32 v116, v236, v151, vcc
	s_lshl_b64 s[14:15], s[14:15], 8
	v_lshlrev_b32_e32 v116, 2, v116
	s_waitcnt lgkmcnt(0)
	v_add_f32_e32 v117, v117, v118
	s_add_u32 s1, s14, s16
	v_mov_b32_e32 v118, v117
	s_nop 1
	v_permlane32_swap_b32 v118, v117
	s_addc_u32 s7, s15, s17
	v_or_b32_e32 v143, s1, v142
	s_ashr_i32 s1, s0, 31
	s_lshl_b64 s[0:1], s[0:1], 2
	v_and_b32_e32 v119, 48, v141
	s_add_u32 s0, s62, s0
	v_mov_b32_e32 v142, s7
	v_cmp_eq_u32_e64 s[16:17], 0, v119
	s_addc_u32 s1, s63, s1
	s_and_saveexec_b64 s[14:15], s[16:17]
	s_cbranch_execz .LBB0_2216
	v_mov_b32_e32 v141, v2
	v_lshl_add_u64 v[120:121], s[20:21], 0, v[140:141]
	global_load_dword v119, v[120:121], off
	s_waitcnt lgkmcnt(0)
	v_add_f32_e32 v117, v117, v118
	s_waitcnt vmcnt(0)
	v_add_f32_e32 v117, v117, v119
	v_fmamk_f32 v117, v117, 0x3c2aaaab, v231
	v_cmp_gt_f32_e32 vcc, s11, v117
	v_mul_f32_e32 v118, 0x4b800000, v117
	s_nop 0
	v_cndmask_b32_e32 v117, v117, v118, vcc
	v_rsq_f32_e32 v117, v117
	s_nop 0
	v_mul_f32_e32 v118, 0x45800000, v117
	v_cndmask_b32_e32 v117, v117, v118, vcc
	v_mad_u64_u32 v[118:119], s[20:21], v143, 48, s[0:1]
	v_mov_b32_e32 v120, v119
	v_mad_u64_u32 v[120:121], s[20:21], v142, 48, v[120:121]
	v_mov_b32_e32 v119, v120
	global_store_dword v[118:119], v117, off

.LBB0_3050:
	s_add_u32 s30, s22, s24
	s_addc_u32 s31, s23, s25
	s_add_u32 s40, s30, 0x100
	s_addc_u32 s41, s31, 0
	s_and_b64 s[28:29], s[26:27], exec
	s_cselect_b32 s43, s19, s41
	s_cselect_b32 s42, s18, s40
	s_add_u32 s24, s14, s24
	s_addc_u32 s25, s15, s25
	s_add_u32 s28, s24, 0x100
	s_addc_u32 s29, s25, 0
	s_add_u32 s24, s42, 0x80
	s_addc_u32 s25, s43, 0
	s_and_b64 s[26:27], s[26:27], exec
	s_cselect_b32 s45, s1, s29
	s_cselect_b32 s44, s9, s28
	s_add_u32 s46, s30, 0x12080
	s_addc_u32 s47, s31, 0
	s_add_i32 s95, s84, s57
	s_add_i32 m0, s63, 0xc000
	s_add_i32 s97, s63, 0xe000
	s_add_i32 s94, s95, 0x2000
	s_add_u32 s40, s44, 0x10000
	s_addc_u32 s41, s45, 0
	s_add_i32 s93, s85, s57
	s_add_i32 s92, s93, 0x2000
	v_add_u32_e32 v152, s84, v1
	s_add_u32 s30, s42, 0x12000
	ds_read_b128 v[140:143], v152
	ds_read_b128 v[144:147], v152 offset:1024
	ds_read_b128 v[148:151], v152 offset:2048
	ds_read_b128 v[152:155], v152 offset:3072
	s_addc_u32 s31, s43, 0
	s_add_u32 s28, s44, 0x80
	s_addc_u32 s29, s45, 0
	s_add_i32 s91, s88, s57
	s_add_i32 s90, s91, 0x2000
	s_add_u32 s26, s44, 0x10080
	s_addc_u32 s27, s45, 0
	s_add_i32 s87, s89, s57
	s_add_i32 s86, s87, 0x2000
	ds_read_b128 v[156:159], v3
	ds_read_b128 v[160:163], v3 offset:1024
	ds_read_b128 v[164:167], v3 offset:2048
	ds_read_b128 v[168:171], v3 offset:3072
	ds_read_b128 v[172:175], v3 offset:4096
	ds_read_b128 v[176:179], v3 offset:5120
	ds_read_b128 v[180:183], v3 offset:6144
	ds_read_b128 v[184:187], v3 offset:7168
	s_nop 0
	global_load_lds_dwordx4 v132, s[46:47]
	s_mov_b32 m0, s97
	s_nop 0
	global_load_lds_dwordx4 v136, s[46:47]
	s_waitcnt lgkmcnt(8)
	s_barrier
	s_waitcnt lgkmcnt(0)
	s_setprio 1
	s_waitcnt lgkmcnt(0)
	v_mfma_f32_16x16x32_bf16 v[128:131], v[140:143], v[156:159], v[128:131]
	v_mfma_f32_16x16x32_bf16 v[124:127], v[148:151], v[156:159], v[124:127]
	v_mfma_f32_16x16x32_bf16 v[112:115], v[140:143], v[164:167], v[112:115]
	v_mfma_f32_16x16x32_bf16 v[108:111], v[148:151], v[164:167], v[108:111]
	v_mfma_f32_16x16x32_bf16 v[96:99], v[140:143], v[172:175], v[96:99]
	v_mfma_f32_16x16x32_bf16 v[92:95], v[148:151], v[172:175], v[92:95]
	v_mfma_f32_16x16x32_bf16 v[80:83], v[140:143], v[180:183], v[80:83]
	v_mfma_f32_16x16x32_bf16 v[76:79], v[148:151], v[180:183], v[76:79]
	v_mfma_f32_16x16x32_bf16 v[128:131], v[144:147], v[160:163], v[128:131]
	v_mfma_f32_16x16x32_bf16 v[124:127], v[152:155], v[160:163], v[124:127]
	v_mfma_f32_16x16x32_bf16 v[112:115], v[144:147], v[168:171], v[112:115]
	v_mfma_f32_16x16x32_bf16 v[108:111], v[152:155], v[168:171], v[108:111]
	v_mfma_f32_16x16x32_bf16 v[96:99], v[144:147], v[176:179], v[96:99]
	v_mfma_f32_16x16x32_bf16 v[92:95], v[152:155], v[176:179], v[92:95]
	v_mfma_f32_16x16x32_bf16 v[80:83], v[144:147], v[184:187], v[80:83]
	v_mfma_f32_16x16x32_bf16 v[76:79], v[152:155], v[184:187], v[76:79]
	s_setprio 0
	s_barrier
	v_add_u32_e32 v196, s85, v1
	s_mov_b32 m0, s95
	ds_read_b128 v[188:191], v196
	ds_read_b128 v[192:195], v196 offset:1024
	ds_read_b128 v[210:213], v196 offset:2048
	ds_read_b128 v[214:217], v196 offset:3072
	s_nop 0
	global_load_lds_dwordx4 v134, s[44:45]
	s_mov_b32 m0, s94
	s_nop 0
	global_load_lds_dwordx4 v138, s[44:45]
	s_barrier
	s_waitcnt lgkmcnt(0)
	s_setprio 1
	s_waitcnt lgkmcnt(0)
	v_mfma_f32_16x16x32_bf16 v[120:123], v[188:191], v[156:159], v[120:123]
	v_mfma_f32_16x16x32_bf16 v[116:119], v[210:213], v[156:159], v[116:119]
	v_mfma_f32_16x16x32_bf16 v[104:107], v[188:191], v[164:167], v[104:107]
	v_mfma_f32_16x16x32_bf16 v[100:103], v[210:213], v[164:167], v[100:103]
	v_mfma_f32_16x16x32_bf16 v[88:91], v[188:191], v[172:175], v[88:91]
	v_mfma_f32_16x16x32_bf16 v[84:87], v[210:213], v[172:175], v[84:87]
	v_mfma_f32_16x16x32_bf16 v[72:75], v[188:191], v[180:183], v[72:75]
	v_mfma_f32_16x16x32_bf16 v[68:71], v[210:213], v[180:183], v[68:71]
	v_mfma_f32_16x16x32_bf16 v[120:123], v[192:195], v[160:163], v[120:123]
	v_mfma_f32_16x16x32_bf16 v[116:119], v[214:217], v[160:163], v[116:119]
	v_mfma_f32_16x16x32_bf16 v[104:107], v[192:195], v[168:171], v[104:107]
	v_mfma_f32_16x16x32_bf16 v[100:103], v[214:217], v[168:171], v[100:103]
	v_mfma_f32_16x16x32_bf16 v[88:91], v[192:195], v[176:179], v[88:91]
	v_mfma_f32_16x16x32_bf16 v[84:87], v[214:217], v[176:179], v[84:87]
	v_mfma_f32_16x16x32_bf16 v[72:75], v[192:195], v[184:187], v[72:75]
	v_mfma_f32_16x16x32_bf16 v[68:71], v[214:217], v[184:187], v[68:71]
	s_setprio 0
	s_mov_b32 m0, s63
	s_barrier
	ds_read_b128 v[156:159], v3 offset:16384
	ds_read_b128 v[160:163], v3 offset:17408
	ds_read_b128 v[164:167], v3 offset:18432
	ds_read_b128 v[168:171], v3 offset:19456
	ds_read_b128 v[172:175], v3 offset:20480
	ds_read_b128 v[176:179], v3 offset:21504
	ds_read_b128 v[180:183], v3 offset:22528
	ds_read_b128 v[184:187], v3 offset:23552
	s_nop 0
	global_load_lds_dwordx4 v132, s[42:43]
	s_mov_b32 m0, s64
	s_nop 0
	global_load_lds_dwordx4 v136, s[42:43]
	s_barrier
	s_waitcnt lgkmcnt(0)
	s_setprio 1
	s_waitcnt lgkmcnt(0)
	v_mfma_f32_16x16x32_bf16 v[64:67], v[140:143], v[156:159], v[64:67]
	v_mfma_f32_16x16x32_bf16 v[60:63], v[148:151], v[156:159], v[60:63]
	v_mfma_f32_16x16x32_bf16 v[48:51], v[140:143], v[164:167], v[48:51]
	v_mfma_f32_16x16x32_bf16 v[44:47], v[148:151], v[164:167], v[44:47]
	v_mfma_f32_16x16x32_bf16 v[32:35], v[140:143], v[172:175], v[32:35]
	v_mfma_f32_16x16x32_bf16 v[28:31], v[148:151], v[172:175], v[28:31]
	v_mfma_f32_16x16x32_bf16 v[16:19], v[140:143], v[180:183], v[16:19]
	v_mfma_f32_16x16x32_bf16 v[12:15], v[148:151], v[180:183], v[12:15]
	v_mfma_f32_16x16x32_bf16 v[64:67], v[144:147], v[160:163], v[64:67]
	v_mfma_f32_16x16x32_bf16 v[60:63], v[152:155], v[160:163], v[60:63]
	v_mfma_f32_16x16x32_bf16 v[48:51], v[144:147], v[168:171], v[48:51]
	v_mfma_f32_16x16x32_bf16 v[44:47], v[152:155], v[168:171], v[44:47]
	v_mfma_f32_16x16x32_bf16 v[32:35], v[144:147], v[176:179], v[32:35]
	v_mfma_f32_16x16x32_bf16 v[28:31], v[152:155], v[176:179], v[28:31]
	v_mfma_f32_16x16x32_bf16 v[16:19], v[144:147], v[184:187], v[16:19]
	v_mfma_f32_16x16x32_bf16 v[12:15], v[152:155], v[184:187], v[12:15]
	s_setprio 0
	s_barrier
	s_mov_b32 m0, s93
	s_nop 0
	global_load_lds_dwordx4 v134, s[40:41]
	s_mov_b32 m0, s92
	s_nop 0
	global_load_lds_dwordx4 v138, s[40:41]
	s_waitcnt vmcnt(6)
	s_barrier
	s_setprio 1
	v_mfma_f32_16x16x32_bf16 v[56:59], v[188:191], v[156:159], v[56:59]
	v_mfma_f32_16x16x32_bf16 v[52:55], v[210:213], v[156:159], v[52:55]
	v_mfma_f32_16x16x32_bf16 v[40:43], v[188:191], v[164:167], v[40:43]
	v_mfma_f32_16x16x32_bf16 v[36:39], v[210:213], v[164:167], v[36:39]
	v_mfma_f32_16x16x32_bf16 v[24:27], v[188:191], v[172:175], v[24:27]
	v_mfma_f32_16x16x32_bf16 v[20:23], v[210:213], v[172:175], v[20:23]
	v_mfma_f32_16x16x32_bf16 v[8:11], v[188:191], v[180:183], v[8:11]
	v_mfma_f32_16x16x32_bf16 v[4:7], v[210:213], v[180:183], v[4:7]
	v_mfma_f32_16x16x32_bf16 v[56:59], v[192:195], v[160:163], v[56:59]
	v_mfma_f32_16x16x32_bf16 v[52:55], v[214:217], v[160:163], v[52:55]
	v_mfma_f32_16x16x32_bf16 v[40:43], v[192:195], v[168:171], v[40:43]
	v_mfma_f32_16x16x32_bf16 v[36:39], v[214:217], v[168:171], v[36:39]
	v_mfma_f32_16x16x32_bf16 v[24:27], v[192:195], v[176:179], v[24:27]
	v_mfma_f32_16x16x32_bf16 v[20:23], v[214:217], v[176:179], v[20:23]
	v_mfma_f32_16x16x32_bf16 v[8:11], v[192:195], v[184:187], v[8:11]
	v_mfma_f32_16x16x32_bf16 v[4:7], v[214:217], v[184:187], v[4:7]
	s_setprio 0
	v_add_u32_e32 v152, s88, v1
	s_barrier
	ds_read_b128 v[140:143], v152
	ds_read_b128 v[144:147], v152 offset:1024
	ds_read_b128 v[148:151], v152 offset:2048
	ds_read_b128 v[152:155], v152 offset:3072
	s_mov_b32 m0, s65
	ds_read_b128 v[156:159], v3 offset:32768
	ds_read_b128 v[160:163], v3 offset:33792
	ds_read_b128 v[164:167], v3 offset:34816
	ds_read_b128 v[168:171], v3 offset:35840
	ds_read_b128 v[172:175], v3 offset:36864
	ds_read_b128 v[176:179], v3 offset:37888
	ds_read_b128 v[180:183], v3 offset:38912
	ds_read_b128 v[184:187], v3 offset:39936
	s_nop 0
	global_load_lds_dwordx4 v132, s[30:31]
	s_mov_b32 m0, s67
	s_nop 0
	global_load_lds_dwordx4 v136, s[30:31]
	s_waitcnt lgkmcnt(8)
	s_barrier
	s_waitcnt lgkmcnt(0)
	s_setprio 1
	s_waitcnt lgkmcnt(0)
	v_mfma_f32_16x16x32_bf16 v[128:131], v[140:143], v[156:159], v[128:131]
	v_mfma_f32_16x16x32_bf16 v[124:127], v[148:151], v[156:159], v[124:127]
	v_mfma_f32_16x16x32_bf16 v[112:115], v[140:143], v[164:167], v[112:115]
	v_mfma_f32_16x16x32_bf16 v[108:111], v[148:151], v[164:167], v[108:111]
	v_mfma_f32_16x16x32_bf16 v[96:99], v[140:143], v[172:175], v[96:99]
	v_mfma_f32_16x16x32_bf16 v[92:95], v[148:151], v[172:175], v[92:95]
	v_mfma_f32_16x16x32_bf16 v[80:83], v[140:143], v[180:183], v[80:83]
	v_mfma_f32_16x16x32_bf16 v[76:79], v[148:151], v[180:183], v[76:79]
	v_mfma_f32_16x16x32_bf16 v[128:131], v[144:147], v[160:163], v[128:131]
	v_mfma_f32_16x16x32_bf16 v[124:127], v[152:155], v[160:163], v[124:127]
	v_mfma_f32_16x16x32_bf16 v[112:115], v[144:147], v[168:171], v[112:115]
	v_mfma_f32_16x16x32_bf16 v[108:111], v[152:155], v[168:171], v[108:111]
	v_mfma_f32_16x16x32_bf16 v[96:99], v[144:147], v[176:179], v[96:99]
	v_mfma_f32_16x16x32_bf16 v[92:95], v[152:155], v[176:179], v[92:95]
	v_mfma_f32_16x16x32_bf16 v[80:83], v[144:147], v[184:187], v[80:83]
	v_mfma_f32_16x16x32_bf16 v[76:79], v[152:155], v[184:187], v[76:79]
	s_setprio 0
	s_barrier
	v_add_u32_e32 v196, s89, v1
	s_mov_b32 m0, s91
	ds_read_b128 v[188:191], v196
	ds_read_b128 v[192:195], v196 offset:1024
	ds_read_b128 v[210:213], v196 offset:2048
	ds_read_b128 v[214:217], v196 offset:3072
	s_nop 0
	global_load_lds_dwordx4 v134, s[28:29]
	s_mov_b32 m0, s90
	s_nop 0
	global_load_lds_dwordx4 v138, s[28:29]
	s_barrier
	s_waitcnt lgkmcnt(0)
	s_setprio 1
	s_waitcnt lgkmcnt(0)
	v_mfma_f32_16x16x32_bf16 v[120:123], v[188:191], v[156:159], v[120:123]
	v_mfma_f32_16x16x32_bf16 v[116:119], v[210:213], v[156:159], v[116:119]
	v_mfma_f32_16x16x32_bf16 v[104:107], v[188:191], v[164:167], v[104:107]
	v_mfma_f32_16x16x32_bf16 v[100:103], v[210:213], v[164:167], v[100:103]
	v_mfma_f32_16x16x32_bf16 v[88:91], v[188:191], v[172:175], v[88:91]
	v_mfma_f32_16x16x32_bf16 v[84:87], v[210:213], v[172:175], v[84:87]
	v_mfma_f32_16x16x32_bf16 v[72:75], v[188:191], v[180:183], v[72:75]
	v_mfma_f32_16x16x32_bf16 v[68:71], v[210:213], v[180:183], v[68:71]
	v_mfma_f32_16x16x32_bf16 v[120:123], v[192:195], v[160:163], v[120:123]
	v_mfma_f32_16x16x32_bf16 v[116:119], v[214:217], v[160:163], v[116:119]
	v_mfma_f32_16x16x32_bf16 v[104:107], v[192:195], v[168:171], v[104:107]
	v_mfma_f32_16x16x32_bf16 v[100:103], v[214:217], v[168:171], v[100:103]
	v_mfma_f32_16x16x32_bf16 v[88:91], v[192:195], v[176:179], v[88:91]
	v_mfma_f32_16x16x32_bf16 v[84:87], v[214:217], v[176:179], v[84:87]
	v_mfma_f32_16x16x32_bf16 v[72:75], v[192:195], v[184:187], v[72:75]
	v_mfma_f32_16x16x32_bf16 v[68:71], v[214:217], v[184:187], v[68:71]
	s_setprio 0
	s_mov_b32 m0, s75
	s_barrier
	ds_read_b128 v[156:159], v3 offset:49152
	ds_read_b128 v[160:163], v3 offset:50176
	ds_read_b128 v[164:167], v3 offset:51200
	ds_read_b128 v[168:171], v3 offset:52224
	ds_read_b128 v[172:175], v3 offset:53248
	ds_read_b128 v[176:179], v3 offset:54272
	ds_read_b128 v[180:183], v3 offset:55296
	ds_read_b128 v[184:187], v3 offset:56320
	s_nop 0
	global_load_lds_dwordx4 v132, s[24:25]
	s_mov_b32 m0, s78
	s_nop 0
	global_load_lds_dwordx4 v136, s[24:25]
	s_barrier
	s_waitcnt lgkmcnt(0)
	s_setprio 1
	s_waitcnt lgkmcnt(0)
	v_mfma_f32_16x16x32_bf16 v[64:67], v[140:143], v[156:159], v[64:67]
	v_mfma_f32_16x16x32_bf16 v[60:63], v[148:151], v[156:159], v[60:63]
	v_mfma_f32_16x16x32_bf16 v[48:51], v[140:143], v[164:167], v[48:51]
	v_mfma_f32_16x16x32_bf16 v[44:47], v[148:151], v[164:167], v[44:47]
	v_mfma_f32_16x16x32_bf16 v[32:35], v[140:143], v[172:175], v[32:35]
	v_mfma_f32_16x16x32_bf16 v[28:31], v[148:151], v[172:175], v[28:31]
	v_mfma_f32_16x16x32_bf16 v[16:19], v[140:143], v[180:183], v[16:19]
	v_mfma_f32_16x16x32_bf16 v[12:15], v[148:151], v[180:183], v[12:15]
	v_mfma_f32_16x16x32_bf16 v[64:67], v[144:147], v[160:163], v[64:67]
	v_mfma_f32_16x16x32_bf16 v[60:63], v[152:155], v[160:163], v[60:63]
	v_mfma_f32_16x16x32_bf16 v[48:51], v[144:147], v[168:171], v[48:51]
	v_mfma_f32_16x16x32_bf16 v[44:47], v[152:155], v[168:171], v[44:47]
	v_mfma_f32_16x16x32_bf16 v[32:35], v[144:147], v[176:179], v[32:35]
	v_mfma_f32_16x16x32_bf16 v[28:31], v[152:155], v[176:179], v[28:31]
	v_mfma_f32_16x16x32_bf16 v[16:19], v[144:147], v[184:187], v[16:19]
	v_mfma_f32_16x16x32_bf16 v[12:15], v[152:155], v[184:187], v[12:15]
	s_setprio 0
	s_barrier
	s_mov_b32 m0, s87
	s_nop 0
	global_load_lds_dwordx4 v134, s[26:27]
	s_mov_b32 m0, s86
	s_nop 0
	global_load_lds_dwordx4 v138, s[26:27]
	s_waitcnt vmcnt(6)
	s_barrier
	s_setprio 1
	v_mfma_f32_16x16x32_bf16 v[56:59], v[188:191], v[156:159], v[56:59]
	v_mfma_f32_16x16x32_bf16 v[52:55], v[210:213], v[156:159], v[52:55]
	v_mfma_f32_16x16x32_bf16 v[40:43], v[188:191], v[164:167], v[40:43]
	v_mfma_f32_16x16x32_bf16 v[36:39], v[210:213], v[164:167], v[36:39]
	v_mfma_f32_16x16x32_bf16 v[24:27], v[188:191], v[172:175], v[24:27]
	v_mfma_f32_16x16x32_bf16 v[20:23], v[210:213], v[172:175], v[20:23]
	v_mfma_f32_16x16x32_bf16 v[8:11], v[188:191], v[180:183], v[8:11]
	v_mfma_f32_16x16x32_bf16 v[4:7], v[210:213], v[180:183], v[4:7]
	v_mfma_f32_16x16x32_bf16 v[56:59], v[192:195], v[160:163], v[56:59]
	v_mfma_f32_16x16x32_bf16 v[52:55], v[214:217], v[160:163], v[52:55]
	v_mfma_f32_16x16x32_bf16 v[40:43], v[192:195], v[168:171], v[40:43]
	v_mfma_f32_16x16x32_bf16 v[36:39], v[214:217], v[168:171], v[36:39]
	v_mfma_f32_16x16x32_bf16 v[24:27], v[192:195], v[176:179], v[24:27]
	v_mfma_f32_16x16x32_bf16 v[20:23], v[214:217], v[176:179], v[20:23]
	v_mfma_f32_16x16x32_bf16 v[8:11], v[192:195], v[184:187], v[8:11]
	v_mfma_f32_16x16x32_bf16 v[4:7], v[214:217], v[184:187], v[4:7]
	s_setprio 0
	s_andn2_b64 vcc, exec, s[16:17]
	s_mov_b64 s[26:27], -1
	s_mov_b64 s[16:17], 0
	s_mov_b64 s[24:25], 0x100
	s_barrier
	s_cbranch_vccz .LBB0_3050
	v_mov_b32_e32 v141, v0
	s_ashr_i32 s1, s0, 31
	v_readfirstlane_b32 s9, v141
	s_bfe_u32 s24, s9, 0x20006
	s_ashr_i32 s9, s9, 2
	s_and_b32 s14, s9, 0xffffffc0
	s_ashr_i32 s15, s14, 31
	s_lshl_b64 s[16:17], s[0:1], 10
	s_add_u32 s9, s68, s16
	s_addc_u32 s23, s72, s17
	s_lshl_b64 s[16:17], s[14:15], 2
	v_and_b32_e32 v142, 15, v141
	s_add_u32 s22, s9, s16
	s_addc_u32 s23, s23, s17
	v_lshlrev_b32_e32 v140, 2, v142
	s_min_u32 s100, s82, 0x7ff
	s_lshl_b32 s100, s100, 10
	v_and_b32_e32 v210, 7, v0
	v_lshlrev_b32_e32 v210, 7, v210
	v_add_u32_e32 v210, s100, v210
	s_mov_b32 s100, s68
	s_mov_b32 s101, s72
	global_load_dword v211, v210, s[100:101]
	global_load_dword v150, v140, s[22:23] offset:64
	global_load_dword v149, v140, s[22:23] offset:128
	global_load_dword v148, v140, s[22:23] offset:192
	global_load_dword v147, v140, s[22:23] offset:512
	global_load_dword v146, v140, s[22:23] offset:576
	global_load_dword v145, v140, s[22:23] offset:640
	global_load_dword v144, v140, s[22:23] offset:704
	v_mul_f32_e32 v129, v129, v129
	v_mul_f32_e32 v125, v125, v125
	v_mul_f32_e32 v121, v121, v121
	v_mul_f32_e32 v117, v117, v117
	v_fmac_f32_e32 v129, v128, v128
	v_mul_f32_e32 v128, v131, v131
	v_fmac_f32_e32 v125, v124, v124
	v_mul_f32_e32 v124, v127, v127
	v_fmac_f32_e32 v121, v120, v120
	v_mul_f32_e32 v120, v123, v123
	v_fmac_f32_e32 v117, v116, v116
	v_mul_f32_e32 v116, v119, v119
	v_fmac_f32_e32 v128, v130, v130
	v_fmac_f32_e32 v124, v126, v126
	v_fmac_f32_e32 v120, v122, v122
	v_fmac_f32_e32 v116, v118, v118
	v_add_f32_e32 v128, v129, v128
	v_add_f32_e32 v124, v125, v124
	v_add_f32_e32 v120, v121, v120
	v_add_f32_e32 v116, v117, v116
	v_add_f32_e32 v124, v128, v124
	v_add_f32_e32 v116, v120, v116
	v_add_f32_e32 v117, v124, v116
	v_mov_b32_e32 v118, v117
	s_nop 1
	v_permlane16_swap_b32 v118, v117
	v_and_b32_e32 v152, 64, v236
	v_xor_b32_e32 v151, 32, v236
	v_add_u32_e32 v152, 64, v152
	v_cmp_lt_i32_e32 vcc, v151, v152
	s_lshl_b32 s9, s83, 2
	s_or_b32 s24, s24, s9
	v_cndmask_b32_e32 v116, v236, v151, vcc
	s_lshl_b64 s[0:1], s[0:1], 8
	v_lshlrev_b32_e32 v116, 2, v116
	s_waitcnt lgkmcnt(0)
	v_add_f32_e32 v117, v117, v118
	s_add_u32 s0, s0, s14
	v_mov_b32_e32 v118, v117
	s_nop 1
	v_permlane32_swap_b32 v118, v117
	s_addc_u32 s1, s1, s15
	s_ashr_i32 s25, s24, 31
	v_or_b32_e32 v143, s0, v142
	v_mov_b32_e32 v142, s1
	s_lshl_b64 s[0:1], s[24:25], 2
	v_and_b32_e32 v119, 48, v141
	s_add_u32 s0, s73, s0
	v_cmp_eq_u32_e64 s[16:17], 0, v119
	s_addc_u32 s1, s74, s1
	s_and_saveexec_b64 s[14:15], s[16:17]
	s_cbranch_execz .LBB0_3053
	v_mov_b32_e32 v141, v2
	v_lshl_add_u64 v[120:121], s[22:23], 0, v[140:141]
	global_load_dword v119, v[120:121], off
	s_waitcnt lgkmcnt(0)
	v_add_f32_e32 v117, v117, v118
	s_waitcnt vmcnt(0)
	v_add_f32_e32 v117, v117, v119
	v_fmamk_f32 v117, v117, 0x3c2aaaab, v231
	v_cmp_gt_f32_e32 vcc, s11, v117
	v_mul_f32_e32 v118, 0x4b800000, v117
	s_nop 0
	v_cndmask_b32_e32 v117, v117, v118, vcc
	v_rsq_f32_e32 v117, v117
	s_nop 0
	v_mul_f32_e32 v118, 0x45800000, v117
	v_cndmask_b32_e32 v117, v117, v118, vcc
	v_mad_u64_u32 v[118:119], s[22:23], v143, 48, s[0:1]
	v_mov_b32_e32 v120, v119
	v_mad_u64_u32 v[120:121], s[22:23], v142, 48, v[120:121]
	v_mov_b32_e32 v119, v120
	global_store_dword v[118:119], v117, off
